# adds in1 natural-layout copy batched and FFN-up epilogue weight loads hoisted above the staging
# speedup vs baseline: 1.0054x; 1.0032x over previous
; #define G_LOADA(kt_) { _Pragma("unroll") for (int i = 0; i < 4; ++i) ra[i] = al(lrow + 64 * i, (kt_) * 64 + lck * 8); }
; #define G_LOADB(kt_) { _Pragma("unroll") for (int i = 0; i < 4; ++i) rb[i] = bl(lrow + 64 * i, (kt_) * 64 + lck * 8); }
; #define G_STOREA(buf_) { bf16_t* nA = sA + (buf_) * 256 * GLD; _Pragma("unroll") for (int i = 0; i < 4; ++i) *(u32x4*)(nA + (lrow + 64 * i) * GLD + lck * 8) = ra[i]; }
; #define G_STOREB(buf_) { bf16_t* nB = sB + (buf_) * 256 * GLD; _Pragma("unroll") for (int i = 0; i < 4; ++i) *(u32x4*)(nB + (lrow + 64 * i) * GLD + lck * 8) = rb[i]; }
; template <class AL, class BL, class EP>
; DI void gemm_tile256(AL al, BL bl, EP ep, int K, char* smem) {
;     ...
;   const int KT = K >> 6;
;     ...
;   G_LOADA(0); G_LOADB(0);
;   __syncthreads();
;   G_STOREA(0); G_STOREB(0);
;   if (KT > 1) G_LOADB(1);
;   __syncthreads();
;   for (int kt = 0; kt < KT; kt += 2) {
;     G_STEP(0, kt);
;     if (kt + 1 >= KT) break;
;     G_STEP(1, kt + 1);
;   }
.Lgk_ph6_loop:
	s_waitcnt lgkmcnt(0)
	v_mfma_f32_32x32x16_bf16 v[112:127], v[188:191], v[156:159], v[112:127]
	ds_read_b128 v[200:203], v199
	ds_read_b128 v[172:175], v155
	v_mfma_f32_32x32x16_bf16 v[96:111], v[192:195], v[156:159], v[96:111]
	ds_read_b128 v[204:207], v199 offset:2048
	ds_read_b128 v[176:179], v155 offset:2048
	v_mfma_f32_32x32x16_bf16 v[80:95], v[188:191], v[160:163], v[80:95]
	ds_read_b128 v[180:183], v155 offset:4096
	ds_read_b128 v[184:187], v155 offset:6144
	v_mfma_f32_32x32x16_bf16 v[64:79], v[192:195], v[160:163], v[64:79]
	s_add_u32 m0, s29, 0x22000
	s_nop 0
	global_load_lds_dwordx4 v[218:219], off
	v_lshl_add_u64 v[218:219], v[218:219], 0, s[10:11]
	v_mfma_f32_32x32x16_bf16 v[48:63], v[188:191], v[164:167], v[48:63]
	v_mfma_f32_32x32x16_bf16 v[32:47], v[192:195], v[164:167], v[32:47]
	v_mfma_f32_32x32x16_bf16 v[16:31], v[188:191], v[168:171], v[16:31]
	v_mfma_f32_32x32x16_bf16 v[0:15], v[192:195], v[168:171], v[0:15]
	s_add_u32 m0, s29, 0x26000
	s_nop 0
	global_load_lds_dwordx4 v[222:223], off
	v_lshl_add_u64 v[222:223], v[222:223], 0, s[10:11]
	s_waitcnt lgkmcnt(0)
	s_waitcnt vmcnt(12)
	s_barrier
	s_waitcnt lgkmcnt(0)
	v_mfma_f32_32x32x16_bf16 v[112:127], v[200:203], v[172:175], v[112:127]
	ds_read_b128 v[188:191], v198 offset:32768
	ds_read_b128 v[156:159], v134 offset:32768
	v_mfma_f32_32x32x16_bf16 v[96:111], v[204:207], v[172:175], v[96:111]
	ds_read_b128 v[192:195], v198 offset:34816
	ds_read_b128 v[160:163], v134 offset:34816
	v_mfma_f32_32x32x16_bf16 v[80:95], v[200:203], v[176:179], v[80:95]
	ds_read_b128 v[164:167], v134 offset:36864
	ds_read_b128 v[168:171], v134 offset:38912
	v_mfma_f32_32x32x16_bf16 v[64:79], v[204:207], v[176:179], v[64:79]
	s_add_u32 m0, s29, 0x0
	s_nop 0
	global_load_lds_dwordx4 v[216:217], off
	v_lshl_add_u64 v[216:217], v[216:217], 0, s[10:11]
	v_mfma_f32_32x32x16_bf16 v[48:63], v[200:203], v[180:183], v[48:63]
	v_mfma_f32_32x32x16_bf16 v[32:47], v[204:207], v[180:183], v[32:47]
	v_mfma_f32_32x32x16_bf16 v[16:31], v[200:203], v[184:187], v[16:31]
	v_mfma_f32_32x32x16_bf16 v[0:15], v[204:207], v[184:187], v[0:15]
	s_add_u32 m0, s29, 0x4000
	s_nop 0
	global_load_lds_dwordx4 v[220:221], off
	v_lshl_add_u64 v[220:221], v[220:221], 0, s[10:11]
	s_waitcnt lgkmcnt(0)
	v_mfma_f32_32x32x16_bf16 v[112:127], v[188:191], v[156:159], v[112:127]
	ds_read_b128 v[200:203], v199 offset:32768
	ds_read_b128 v[172:175], v155 offset:32768
	v_mfma_f32_32x32x16_bf16 v[96:111], v[192:195], v[156:159], v[96:111]
	ds_read_b128 v[204:207], v199 offset:34816
	ds_read_b128 v[176:179], v155 offset:34816
	v_mfma_f32_32x32x16_bf16 v[80:95], v[188:191], v[160:163], v[80:95]
	ds_read_b128 v[180:183], v155 offset:36864
	ds_read_b128 v[184:187], v155 offset:38912
	v_mfma_f32_32x32x16_bf16 v[64:79], v[192:195], v[160:163], v[64:79]
	s_add_u32 m0, s29, 0x2000
	s_nop 0
	global_load_lds_dwordx4 v[218:219], off
	v_lshl_add_u64 v[218:219], v[218:219], 0, s[10:11]
	v_mfma_f32_32x32x16_bf16 v[48:63], v[188:191], v[164:167], v[48:63]
	v_mfma_f32_32x32x16_bf16 v[32:47], v[192:195], v[164:167], v[32:47]
	v_mfma_f32_32x32x16_bf16 v[16:31], v[188:191], v[168:171], v[16:31]
	v_mfma_f32_32x32x16_bf16 v[0:15], v[192:195], v[168:171], v[0:15]
	s_add_u32 m0, s29, 0x6000
	s_nop 0
	global_load_lds_dwordx4 v[222:223], off
	v_lshl_add_u64 v[222:223], v[222:223], 0, s[10:11]
	s_waitcnt lgkmcnt(0)
	s_waitcnt vmcnt(12)
	s_barrier
	s_waitcnt lgkmcnt(0)
	v_mfma_f32_32x32x16_bf16 v[112:127], v[200:203], v[172:175], v[112:127]
	ds_read_b128 v[188:191], v210
	ds_read_b128 v[156:159], v208
	v_mfma_f32_32x32x16_bf16 v[96:111], v[204:207], v[172:175], v[96:111]
	ds_read_b128 v[192:195], v210 offset:2048
	ds_read_b128 v[160:163], v208 offset:2048
	v_mfma_f32_32x32x16_bf16 v[80:95], v[200:203], v[176:179], v[80:95]
	ds_read_b128 v[164:167], v208 offset:4096
	ds_read_b128 v[168:171], v208 offset:6144
	v_mfma_f32_32x32x16_bf16 v[64:79], v[204:207], v[176:179], v[64:79]
	s_add_u32 m0, s29, 0x8000
	s_nop 0
	global_load_lds_dwordx4 v[216:217], off
	v_lshl_add_u64 v[216:217], v[216:217], 0, s[10:11]
	v_mfma_f32_32x32x16_bf16 v[48:63], v[200:203], v[180:183], v[48:63]
	v_mfma_f32_32x32x16_bf16 v[32:47], v[204:207], v[180:183], v[32:47]
	v_mfma_f32_32x32x16_bf16 v[16:31], v[200:203], v[184:187], v[16:31]
	v_mfma_f32_32x32x16_bf16 v[0:15], v[204:207], v[184:187], v[0:15]
	s_add_u32 m0, s29, 0xc000
	s_nop 0
	global_load_lds_dwordx4 v[220:221], off
	v_lshl_add_u64 v[220:221], v[220:221], 0, s[10:11]
	s_waitcnt lgkmcnt(0)
	v_mfma_f32_32x32x16_bf16 v[112:127], v[188:191], v[156:159], v[112:127]
	ds_read_b128 v[200:203], v211
	ds_read_b128 v[172:175], v209
	v_mfma_f32_32x32x16_bf16 v[96:111], v[192:195], v[156:159], v[96:111]
	ds_read_b128 v[204:207], v211 offset:2048
	ds_read_b128 v[176:179], v209 offset:2048
	v_mfma_f32_32x32x16_bf16 v[80:95], v[188:191], v[160:163], v[80:95]
	ds_read_b128 v[180:183], v209 offset:4096
	ds_read_b128 v[184:187], v209 offset:6144
	v_mfma_f32_32x32x16_bf16 v[64:79], v[192:195], v[160:163], v[64:79]
	s_add_u32 m0, s29, 0xa000
	s_nop 0
	global_load_lds_dwordx4 v[218:219], off
	v_lshl_add_u64 v[218:219], v[218:219], 0, s[10:11]
	v_mfma_f32_32x32x16_bf16 v[48:63], v[188:191], v[164:167], v[48:63]
	v_mfma_f32_32x32x16_bf16 v[32:47], v[192:195], v[164:167], v[32:47]
	v_mfma_f32_32x32x16_bf16 v[16:31], v[188:191], v[168:171], v[16:31]
	v_mfma_f32_32x32x16_bf16 v[0:15], v[192:195], v[168:171], v[0:15]
	s_add_u32 m0, s29, 0xe000
	s_nop 0
	global_load_lds_dwordx4 v[222:223], off
	v_lshl_add_u64 v[222:223], v[222:223], 0, s[10:11]
	s_waitcnt lgkmcnt(0)
	s_waitcnt vmcnt(12)
	s_barrier
; #define G_LOADA(kt_) { _Pragma("unroll") for (int i = 0; i < 4; ++i) ra[i] = al(lrow + 64 * i, (kt_) * 64 + lck * 8); }
; #define G_LOADB(kt_) { _Pragma("unroll") for (int i = 0; i < 4; ++i) rb[i] = bl(lrow + 64 * i, (kt_) * 64 + lck * 8); }
; #define G_STOREA(buf_) { bf16_t* nA = sA + (buf_) * 256 * GLD; _Pragma("unroll") for (int i = 0; i < 4; ++i) *(u32x4*)(nA + (lrow + 64 * i) * GLD + lck * 8) = ra[i]; }
; #define G_STOREB(buf_) { bf16_t* nB = sB + (buf_) * 256 * GLD; _Pragma("unroll") for (int i = 0; i < 4; ++i) *(u32x4*)(nB + (lrow + 64 * i) * GLD + lck * 8) = rb[i]; }
; template <class AL, class BL, class EP>
; DI void gemm_tile256(AL al, BL bl, EP ep, int K, char* smem) {
;     ...
;   G_LOADA(0); G_LOADB(0);
;   __syncthreads();
;   G_STOREA(0); G_STOREB(0);
;   if (KT > 1) G_LOADB(1);
;   __syncthreads();
;   for (int kt = 0; kt < KT; kt += 2) {
;     G_STEP(0, kt);
;     if (kt + 1 >= KT) break;
;     G_STEP(1, kt + 1);
;   }
	s_waitcnt lgkmcnt(0)
	v_mfma_f32_32x32x16_bf16 v[112:127], v[200:203], v[172:175], v[112:127]
	ds_read_b128 v[188:191], v210 offset:32768
	ds_read_b128 v[156:159], v208 offset:32768
	v_mfma_f32_32x32x16_bf16 v[96:111], v[204:207], v[172:175], v[96:111]
	ds_read_b128 v[192:195], v210 offset:34816
	ds_read_b128 v[160:163], v208 offset:34816
	v_mfma_f32_32x32x16_bf16 v[80:95], v[200:203], v[176:179], v[80:95]
	ds_read_b128 v[164:167], v208 offset:36864
	ds_read_b128 v[168:171], v208 offset:38912
	v_mfma_f32_32x32x16_bf16 v[64:79], v[204:207], v[176:179], v[64:79]
	s_add_u32 m0, s29, 0x10000
	s_nop 0
	global_load_lds_dwordx4 v[216:217], off
	v_lshl_add_u64 v[216:217], v[216:217], 0, s[10:11]
	v_mfma_f32_32x32x16_bf16 v[48:63], v[200:203], v[180:183], v[48:63]
	v_mfma_f32_32x32x16_bf16 v[32:47], v[204:207], v[180:183], v[32:47]
	v_mfma_f32_32x32x16_bf16 v[16:31], v[200:203], v[184:187], v[16:31]
	v_mfma_f32_32x32x16_bf16 v[0:15], v[204:207], v[184:187], v[0:15]
	s_add_u32 m0, s29, 0x14000
	s_nop 0
	global_load_lds_dwordx4 v[220:221], off
	v_lshl_add_u64 v[220:221], v[220:221], 0, s[10:11]
	s_waitcnt lgkmcnt(0)
	v_mfma_f32_32x32x16_bf16 v[112:127], v[188:191], v[156:159], v[112:127]
	ds_read_b128 v[200:203], v211 offset:32768
	ds_read_b128 v[172:175], v209 offset:32768
	v_mfma_f32_32x32x16_bf16 v[96:111], v[192:195], v[156:159], v[96:111]
	ds_read_b128 v[204:207], v211 offset:34816
	ds_read_b128 v[176:179], v209 offset:34816
	v_mfma_f32_32x32x16_bf16 v[80:95], v[188:191], v[160:163], v[80:95]
	ds_read_b128 v[180:183], v209 offset:36864
	ds_read_b128 v[184:187], v209 offset:38912
	v_mfma_f32_32x32x16_bf16 v[64:79], v[192:195], v[160:163], v[64:79]
	s_add_u32 m0, s29, 0x12000
	s_nop 0
	global_load_lds_dwordx4 v[218:219], off
	v_lshl_add_u64 v[218:219], v[218:219], 0, s[10:11]
	v_mfma_f32_32x32x16_bf16 v[48:63], v[188:191], v[164:167], v[48:63]
	v_mfma_f32_32x32x16_bf16 v[32:47], v[192:195], v[164:167], v[32:47]
	v_mfma_f32_32x32x16_bf16 v[16:31], v[188:191], v[168:171], v[16:31]
	v_mfma_f32_32x32x16_bf16 v[0:15], v[192:195], v[168:171], v[0:15]
	s_add_u32 m0, s29, 0x16000
	s_nop 0
	global_load_lds_dwordx4 v[222:223], off
	v_lshl_add_u64 v[222:223], v[222:223], 0, s[10:11]
	s_waitcnt lgkmcnt(0)
	s_waitcnt vmcnt(12)
	s_barrier
	s_waitcnt lgkmcnt(0)
	v_mfma_f32_32x32x16_bf16 v[112:127], v[200:203], v[172:175], v[112:127]
	ds_read_b128 v[188:191], v214
	ds_read_b128 v[156:159], v212
	v_mfma_f32_32x32x16_bf16 v[96:111], v[204:207], v[172:175], v[96:111]
	ds_read_b128 v[192:195], v214 offset:2048
	ds_read_b128 v[160:163], v212 offset:2048
	v_mfma_f32_32x32x16_bf16 v[80:95], v[200:203], v[176:179], v[80:95]
	ds_read_b128 v[164:167], v212 offset:4096
	ds_read_b128 v[168:171], v212 offset:6144
	v_mfma_f32_32x32x16_bf16 v[64:79], v[204:207], v[176:179], v[64:79]
	s_add_u32 m0, s29, 0x18000
	s_nop 0
	global_load_lds_dwordx4 v[216:217], off
	v_lshl_add_u64 v[216:217], v[216:217], 0, s[10:11]
	v_mfma_f32_32x32x16_bf16 v[48:63], v[200:203], v[180:183], v[48:63]
	v_mfma_f32_32x32x16_bf16 v[32:47], v[204:207], v[180:183], v[32:47]
	v_mfma_f32_32x32x16_bf16 v[16:31], v[200:203], v[184:187], v[16:31]
	v_mfma_f32_32x32x16_bf16 v[0:15], v[204:207], v[184:187], v[0:15]
	s_add_u32 m0, s29, 0x1c000
	s_nop 0
	global_load_lds_dwordx4 v[220:221], off
	v_lshl_add_u64 v[220:221], v[220:221], 0, s[10:11]
	s_waitcnt lgkmcnt(0)
	v_mfma_f32_32x32x16_bf16 v[112:127], v[188:191], v[156:159], v[112:127]
	ds_read_b128 v[200:203], v215
	ds_read_b128 v[172:175], v213
	v_mfma_f32_32x32x16_bf16 v[96:111], v[192:195], v[156:159], v[96:111]
	ds_read_b128 v[204:207], v215 offset:2048
	ds_read_b128 v[176:179], v213 offset:2048
	v_mfma_f32_32x32x16_bf16 v[80:95], v[188:191], v[160:163], v[80:95]
	ds_read_b128 v[180:183], v213 offset:4096
	ds_read_b128 v[184:187], v213 offset:6144
	v_mfma_f32_32x32x16_bf16 v[64:79], v[192:195], v[160:163], v[64:79]
	s_add_u32 m0, s29, 0x1a000
	s_nop 0
	global_load_lds_dwordx4 v[218:219], off
	v_lshl_add_u64 v[218:219], v[218:219], 0, s[10:11]
	v_mfma_f32_32x32x16_bf16 v[48:63], v[188:191], v[164:167], v[48:63]
	v_mfma_f32_32x32x16_bf16 v[32:47], v[192:195], v[164:167], v[32:47]
	v_mfma_f32_32x32x16_bf16 v[16:31], v[188:191], v[168:171], v[16:31]
	v_mfma_f32_32x32x16_bf16 v[0:15], v[192:195], v[168:171], v[0:15]
	s_add_u32 m0, s29, 0x1e000
	s_nop 0
	global_load_lds_dwordx4 v[222:223], off
	v_lshl_add_u64 v[222:223], v[222:223], 0, s[10:11]
	s_waitcnt lgkmcnt(0)
	s_waitcnt vmcnt(12)
	s_barrier
	s_waitcnt lgkmcnt(0)
	v_mfma_f32_32x32x16_bf16 v[112:127], v[200:203], v[172:175], v[112:127]
	ds_read_b128 v[188:191], v198
	ds_read_b128 v[156:159], v134
	v_mfma_f32_32x32x16_bf16 v[96:111], v[204:207], v[172:175], v[96:111]
	ds_read_b128 v[192:195], v198 offset:2048
	ds_read_b128 v[160:163], v134 offset:2048
	v_mfma_f32_32x32x16_bf16 v[80:95], v[200:203], v[176:179], v[80:95]
	ds_read_b128 v[164:167], v134 offset:4096
	ds_read_b128 v[168:171], v134 offset:6144
	v_mfma_f32_32x32x16_bf16 v[64:79], v[204:207], v[176:179], v[64:79]
	s_add_u32 m0, s29, 0x20000
	s_nop 0
	global_load_lds_dwordx4 v[216:217], off
	v_lshl_add_u64 v[216:217], v[216:217], 0, s[10:11]
	v_mfma_f32_32x32x16_bf16 v[48:63], v[200:203], v[180:183], v[48:63]
	v_mfma_f32_32x32x16_bf16 v[32:47], v[204:207], v[180:183], v[32:47]
	v_mfma_f32_32x32x16_bf16 v[16:31], v[200:203], v[184:187], v[16:31]
	v_mfma_f32_32x32x16_bf16 v[0:15], v[204:207], v[184:187], v[0:15]
	s_add_u32 m0, s29, 0x24000
	s_nop 0
	global_load_lds_dwordx4 v[220:221], off
	v_lshl_add_u64 v[220:221], v[220:221], 0, s[10:11]
	s_sub_u32 s30, s30, 1
	s_cmp_lg_u32 s30, 0
	s_cbranch_scc1 .Lgk_ph6_loop
; #define G_LOADA(kt_) { _Pragma("unroll") for (int i = 0; i < 4; ++i) ra[i] = al(lrow + 64 * i, (kt_) * 64 + lck * 8); }
; #define G_LOADB(kt_) { _Pragma("unroll") for (int i = 0; i < 4; ++i) rb[i] = bl(lrow + 64 * i, (kt_) * 64 + lck * 8); }
; #define G_STOREA(buf_) { bf16_t* nA = sA + (buf_) * 256 * GLD; _Pragma("unroll") for (int i = 0; i < 4; ++i) *(u32x4*)(nA + (lrow + 64 * i) * GLD + lck * 8) = ra[i]; }
; #define G_STOREB(buf_) { bf16_t* nB = sB + (buf_) * 256 * GLD; _Pragma("unroll") for (int i = 0; i < 4; ++i) *(u32x4*)(nB + (lrow + 64 * i) * GLD + lck * 8) = rb[i]; }
; template <class AL, class BL, class EP>
; DI void gemm_tile256(AL al, BL bl, EP ep, int K, char* smem) {
;     ...
;   G_LOADA(0); G_LOADB(0);
;   __syncthreads();
;   G_STOREA(0); G_STOREB(0);
;   if (KT > 1) G_LOADB(1);
;   __syncthreads();
;   for (int kt = 0; kt < KT; kt += 2) {
;     G_STEP(0, kt);
;     if (kt + 1 >= KT) break;
;     G_STEP(1, kt + 1);
;   }
	s_waitcnt lgkmcnt(0)
	v_mfma_f32_32x32x16_bf16 v[112:127], v[188:191], v[156:159], v[112:127]
	ds_read_b128 v[200:203], v199
	ds_read_b128 v[172:175], v155
	v_mfma_f32_32x32x16_bf16 v[96:111], v[192:195], v[156:159], v[96:111]
	ds_read_b128 v[204:207], v199 offset:2048
	ds_read_b128 v[176:179], v155 offset:2048
	v_mfma_f32_32x32x16_bf16 v[80:95], v[188:191], v[160:163], v[80:95]
	ds_read_b128 v[180:183], v155 offset:4096
	ds_read_b128 v[184:187], v155 offset:6144
	v_mfma_f32_32x32x16_bf16 v[64:79], v[192:195], v[160:163], v[64:79]
	s_add_u32 m0, s29, 0x22000
	s_nop 0
	global_load_lds_dwordx4 v[218:219], off
	v_lshl_add_u64 v[218:219], v[218:219], 0, s[10:11]
	v_mfma_f32_32x32x16_bf16 v[48:63], v[188:191], v[164:167], v[48:63]
	v_mfma_f32_32x32x16_bf16 v[32:47], v[192:195], v[164:167], v[32:47]
	v_mfma_f32_32x32x16_bf16 v[16:31], v[188:191], v[168:171], v[16:31]
	v_mfma_f32_32x32x16_bf16 v[0:15], v[192:195], v[168:171], v[0:15]
	s_add_u32 m0, s29, 0x26000
	s_nop 0
	global_load_lds_dwordx4 v[222:223], off
	v_lshl_add_u64 v[222:223], v[222:223], 0, s[10:11]
	s_waitcnt lgkmcnt(0)
	s_waitcnt vmcnt(12)
	s_barrier
	s_waitcnt lgkmcnt(0)
	v_mfma_f32_32x32x16_bf16 v[112:127], v[200:203], v[172:175], v[112:127]
	ds_read_b128 v[188:191], v198 offset:32768
	ds_read_b128 v[156:159], v134 offset:32768
	v_mfma_f32_32x32x16_bf16 v[96:111], v[204:207], v[172:175], v[96:111]
	ds_read_b128 v[192:195], v198 offset:34816
	ds_read_b128 v[160:163], v134 offset:34816
	v_mfma_f32_32x32x16_bf16 v[80:95], v[200:203], v[176:179], v[80:95]
	ds_read_b128 v[164:167], v134 offset:36864
	ds_read_b128 v[168:171], v134 offset:38912
	v_mfma_f32_32x32x16_bf16 v[64:79], v[204:207], v[176:179], v[64:79]
	s_add_u32 m0, s29, 0x0
	s_nop 0
	global_load_lds_dwordx4 v[216:217], off
	v_lshl_add_u64 v[216:217], v[216:217], 0, s[10:11]
	v_mfma_f32_32x32x16_bf16 v[48:63], v[200:203], v[180:183], v[48:63]
	v_mfma_f32_32x32x16_bf16 v[32:47], v[204:207], v[180:183], v[32:47]
	v_mfma_f32_32x32x16_bf16 v[16:31], v[200:203], v[184:187], v[16:31]
	v_mfma_f32_32x32x16_bf16 v[0:15], v[204:207], v[184:187], v[0:15]
	s_add_u32 m0, s29, 0x4000
	s_nop 0
	global_load_lds_dwordx4 v[220:221], off
	v_lshl_add_u64 v[220:221], v[220:221], 0, s[10:11]
	s_waitcnt lgkmcnt(0)
	v_mfma_f32_32x32x16_bf16 v[112:127], v[188:191], v[156:159], v[112:127]
	ds_read_b128 v[200:203], v199 offset:32768
	ds_read_b128 v[172:175], v155 offset:32768
	v_mfma_f32_32x32x16_bf16 v[96:111], v[192:195], v[156:159], v[96:111]
	ds_read_b128 v[204:207], v199 offset:34816
	ds_read_b128 v[176:179], v155 offset:34816
	v_mfma_f32_32x32x16_bf16 v[80:95], v[188:191], v[160:163], v[80:95]
	ds_read_b128 v[180:183], v155 offset:36864
	ds_read_b128 v[184:187], v155 offset:38912
	v_mfma_f32_32x32x16_bf16 v[64:79], v[192:195], v[160:163], v[64:79]
	s_add_u32 m0, s29, 0x2000
	s_nop 0
	global_load_lds_dwordx4 v[218:219], off
	v_lshl_add_u64 v[218:219], v[218:219], 0, s[10:11]
	v_mfma_f32_32x32x16_bf16 v[48:63], v[188:191], v[164:167], v[48:63]
	v_mfma_f32_32x32x16_bf16 v[32:47], v[192:195], v[164:167], v[32:47]
	v_mfma_f32_32x32x16_bf16 v[16:31], v[188:191], v[168:171], v[16:31]
	v_mfma_f32_32x32x16_bf16 v[0:15], v[192:195], v[168:171], v[0:15]
	s_add_u32 m0, s29, 0x6000
	s_nop 0
	global_load_lds_dwordx4 v[222:223], off
	v_lshl_add_u64 v[222:223], v[222:223], 0, s[10:11]
	s_waitcnt lgkmcnt(0)
	s_waitcnt vmcnt(12)
	s_barrier
	s_waitcnt lgkmcnt(0)
	v_mfma_f32_32x32x16_bf16 v[112:127], v[200:203], v[172:175], v[112:127]
	ds_read_b128 v[188:191], v210
	ds_read_b128 v[156:159], v208
	v_mfma_f32_32x32x16_bf16 v[96:111], v[204:207], v[172:175], v[96:111]
	ds_read_b128 v[192:195], v210 offset:2048
	ds_read_b128 v[160:163], v208 offset:2048
	v_mfma_f32_32x32x16_bf16 v[80:95], v[200:203], v[176:179], v[80:95]
	ds_read_b128 v[164:167], v208 offset:4096
	ds_read_b128 v[168:171], v208 offset:6144
	v_mfma_f32_32x32x16_bf16 v[64:79], v[204:207], v[176:179], v[64:79]
	s_add_u32 m0, s29, 0x8000
	s_nop 0
	global_load_lds_dwordx4 v[216:217], off
	v_lshl_add_u64 v[216:217], v[216:217], 0, s[10:11]
	v_mfma_f32_32x32x16_bf16 v[48:63], v[200:203], v[180:183], v[48:63]
	v_mfma_f32_32x32x16_bf16 v[32:47], v[204:207], v[180:183], v[32:47]
	v_mfma_f32_32x32x16_bf16 v[16:31], v[200:203], v[184:187], v[16:31]
	v_mfma_f32_32x32x16_bf16 v[0:15], v[204:207], v[184:187], v[0:15]
	s_add_u32 m0, s29, 0xc000
	s_nop 0
	global_load_lds_dwordx4 v[220:221], off
	v_lshl_add_u64 v[220:221], v[220:221], 0, s[10:11]
	s_waitcnt lgkmcnt(0)
	v_mfma_f32_32x32x16_bf16 v[112:127], v[188:191], v[156:159], v[112:127]
	ds_read_b128 v[200:203], v211
	ds_read_b128 v[172:175], v209
	v_mfma_f32_32x32x16_bf16 v[96:111], v[192:195], v[156:159], v[96:111]
	ds_read_b128 v[204:207], v211 offset:2048
	ds_read_b128 v[176:179], v209 offset:2048
	v_mfma_f32_32x32x16_bf16 v[80:95], v[188:191], v[160:163], v[80:95]
	ds_read_b128 v[180:183], v209 offset:4096
	ds_read_b128 v[184:187], v209 offset:6144
	v_mfma_f32_32x32x16_bf16 v[64:79], v[192:195], v[160:163], v[64:79]
	s_add_u32 m0, s29, 0xa000
	s_nop 0
	global_load_lds_dwordx4 v[218:219], off
	v_lshl_add_u64 v[218:219], v[218:219], 0, s[10:11]
	v_mfma_f32_32x32x16_bf16 v[48:63], v[188:191], v[164:167], v[48:63]
	v_mfma_f32_32x32x16_bf16 v[32:47], v[192:195], v[164:167], v[32:47]
	v_mfma_f32_32x32x16_bf16 v[16:31], v[188:191], v[168:171], v[16:31]
	v_mfma_f32_32x32x16_bf16 v[0:15], v[192:195], v[168:171], v[0:15]
	s_add_u32 m0, s29, 0xe000
	s_nop 0
	global_load_lds_dwordx4 v[222:223], off
	v_lshl_add_u64 v[222:223], v[222:223], 0, s[10:11]
	s_waitcnt lgkmcnt(0)
	s_waitcnt vmcnt(12)
	s_barrier
; #define G_LOADA(kt_) { _Pragma("unroll") for (int i = 0; i < 4; ++i) ra[i] = al(lrow + 64 * i, (kt_) * 64 + lck * 8); }
; #define G_LOADB(kt_) { _Pragma("unroll") for (int i = 0; i < 4; ++i) rb[i] = bl(lrow + 64 * i, (kt_) * 64 + lck * 8); }
; #define G_STOREA(buf_) { bf16_t* nA = sA + (buf_) * 256 * GLD; _Pragma("unroll") for (int i = 0; i < 4; ++i) *(u32x4*)(nA + (lrow + 64 * i) * GLD + lck * 8) = ra[i]; }
; #define G_STOREB(buf_) { bf16_t* nB = sB + (buf_) * 256 * GLD; _Pragma("unroll") for (int i = 0; i < 4; ++i) *(u32x4*)(nB + (lrow + 64 * i) * GLD + lck * 8) = rb[i]; }
; template <class AL, class BL, class EP>
; DI void gemm_tile256(AL al, BL bl, EP ep, int K, char* smem) {
;     ...
;   G_LOADA(0); G_LOADB(0);
;   __syncthreads();
;   G_STOREA(0); G_STOREB(0);
;   if (KT > 1) G_LOADB(1);
;   __syncthreads();
;   for (int kt = 0; kt < KT; kt += 2) {
;     G_STEP(0, kt);
;     if (kt + 1 >= KT) break;
;     G_STEP(1, kt + 1);
;   }
	s_waitcnt lgkmcnt(0)
	v_mfma_f32_32x32x16_bf16 v[112:127], v[200:203], v[172:175], v[112:127]
	ds_read_b128 v[188:191], v210 offset:32768
	ds_read_b128 v[156:159], v208 offset:32768
	v_mfma_f32_32x32x16_bf16 v[96:111], v[204:207], v[172:175], v[96:111]
	ds_read_b128 v[192:195], v210 offset:34816
	ds_read_b128 v[160:163], v208 offset:34816
	v_mfma_f32_32x32x16_bf16 v[80:95], v[200:203], v[176:179], v[80:95]
	ds_read_b128 v[164:167], v208 offset:36864
	ds_read_b128 v[168:171], v208 offset:38912
	v_mfma_f32_32x32x16_bf16 v[64:79], v[204:207], v[176:179], v[64:79]
	v_mfma_f32_32x32x16_bf16 v[48:63], v[200:203], v[180:183], v[48:63]
	v_mfma_f32_32x32x16_bf16 v[32:47], v[204:207], v[180:183], v[32:47]
	v_mfma_f32_32x32x16_bf16 v[16:31], v[200:203], v[184:187], v[16:31]
	v_mfma_f32_32x32x16_bf16 v[0:15], v[204:207], v[184:187], v[0:15]
	s_waitcnt lgkmcnt(0)
	v_mfma_f32_32x32x16_bf16 v[112:127], v[188:191], v[156:159], v[112:127]
	ds_read_b128 v[200:203], v211 offset:32768
	ds_read_b128 v[172:175], v209 offset:32768
	v_mfma_f32_32x32x16_bf16 v[96:111], v[192:195], v[156:159], v[96:111]
	ds_read_b128 v[204:207], v211 offset:34816
	ds_read_b128 v[176:179], v209 offset:34816
	v_mfma_f32_32x32x16_bf16 v[80:95], v[188:191], v[160:163], v[80:95]
	ds_read_b128 v[180:183], v209 offset:36864
	ds_read_b128 v[184:187], v209 offset:38912
	v_mfma_f32_32x32x16_bf16 v[64:79], v[192:195], v[160:163], v[64:79]
	v_mfma_f32_32x32x16_bf16 v[48:63], v[188:191], v[164:167], v[48:63]
	v_mfma_f32_32x32x16_bf16 v[32:47], v[192:195], v[164:167], v[32:47]
	v_mfma_f32_32x32x16_bf16 v[16:31], v[188:191], v[168:171], v[16:31]
	v_mfma_f32_32x32x16_bf16 v[0:15], v[192:195], v[168:171], v[0:15]
	s_waitcnt lgkmcnt(0)
	s_waitcnt vmcnt(8)
	s_barrier
	s_waitcnt lgkmcnt(0)
	v_mfma_f32_32x32x16_bf16 v[112:127], v[200:203], v[172:175], v[112:127]
	ds_read_b128 v[188:191], v214
	ds_read_b128 v[156:159], v212
	v_mfma_f32_32x32x16_bf16 v[96:111], v[204:207], v[172:175], v[96:111]
	ds_read_b128 v[192:195], v214 offset:2048
	ds_read_b128 v[160:163], v212 offset:2048
	v_mfma_f32_32x32x16_bf16 v[80:95], v[200:203], v[176:179], v[80:95]
	ds_read_b128 v[164:167], v212 offset:4096
	ds_read_b128 v[168:171], v212 offset:6144
	v_mfma_f32_32x32x16_bf16 v[64:79], v[204:207], v[176:179], v[64:79]
	v_mfma_f32_32x32x16_bf16 v[48:63], v[200:203], v[180:183], v[48:63]
	v_mfma_f32_32x32x16_bf16 v[32:47], v[204:207], v[180:183], v[32:47]
	v_mfma_f32_32x32x16_bf16 v[16:31], v[200:203], v[184:187], v[16:31]
	v_mfma_f32_32x32x16_bf16 v[0:15], v[204:207], v[184:187], v[0:15]
	s_waitcnt lgkmcnt(0)
	v_mfma_f32_32x32x16_bf16 v[112:127], v[188:191], v[156:159], v[112:127]
	ds_read_b128 v[200:203], v215
	ds_read_b128 v[172:175], v213
	v_mfma_f32_32x32x16_bf16 v[96:111], v[192:195], v[156:159], v[96:111]
	ds_read_b128 v[204:207], v215 offset:2048
	ds_read_b128 v[176:179], v213 offset:2048
	v_mfma_f32_32x32x16_bf16 v[80:95], v[188:191], v[160:163], v[80:95]
	ds_read_b128 v[180:183], v213 offset:4096
	ds_read_b128 v[184:187], v213 offset:6144
	v_mfma_f32_32x32x16_bf16 v[64:79], v[192:195], v[160:163], v[64:79]
	v_mfma_f32_32x32x16_bf16 v[48:63], v[188:191], v[164:167], v[48:63]
	v_mfma_f32_32x32x16_bf16 v[32:47], v[192:195], v[164:167], v[32:47]
	v_mfma_f32_32x32x16_bf16 v[16:31], v[188:191], v[168:171], v[16:31]
	v_mfma_f32_32x32x16_bf16 v[0:15], v[192:195], v[168:171], v[0:15]
	s_waitcnt lgkmcnt(0)
	s_waitcnt vmcnt(4)
	s_barrier
	s_waitcnt lgkmcnt(0)
	v_mfma_f32_32x32x16_bf16 v[112:127], v[200:203], v[172:175], v[112:127]
	ds_read_b128 v[188:191], v198
	ds_read_b128 v[156:159], v134
	v_mfma_f32_32x32x16_bf16 v[96:111], v[204:207], v[172:175], v[96:111]
	ds_read_b128 v[192:195], v198 offset:2048
	ds_read_b128 v[160:163], v134 offset:2048
	v_mfma_f32_32x32x16_bf16 v[80:95], v[200:203], v[176:179], v[80:95]
	ds_read_b128 v[164:167], v134 offset:4096
	ds_read_b128 v[168:171], v134 offset:6144
	v_mfma_f32_32x32x16_bf16 v[64:79], v[204:207], v[176:179], v[64:79]
	v_mfma_f32_32x32x16_bf16 v[48:63], v[200:203], v[180:183], v[48:63]
	v_mfma_f32_32x32x16_bf16 v[32:47], v[204:207], v[180:183], v[32:47]
	v_mfma_f32_32x32x16_bf16 v[16:31], v[200:203], v[184:187], v[16:31]
	v_mfma_f32_32x32x16_bf16 v[0:15], v[204:207], v[184:187], v[0:15]
	s_waitcnt lgkmcnt(0)
	v_mfma_f32_32x32x16_bf16 v[112:127], v[188:191], v[156:159], v[112:127]
	ds_read_b128 v[200:203], v199
	ds_read_b128 v[172:175], v155
	v_mfma_f32_32x32x16_bf16 v[96:111], v[192:195], v[156:159], v[96:111]
	ds_read_b128 v[204:207], v199 offset:2048
	ds_read_b128 v[176:179], v155 offset:2048
	v_mfma_f32_32x32x16_bf16 v[80:95], v[188:191], v[160:163], v[80:95]
	ds_read_b128 v[180:183], v155 offset:4096
	ds_read_b128 v[184:187], v155 offset:6144
	v_mfma_f32_32x32x16_bf16 v[64:79], v[192:195], v[160:163], v[64:79]
	v_mfma_f32_32x32x16_bf16 v[48:63], v[188:191], v[164:167], v[48:63]
	v_mfma_f32_32x32x16_bf16 v[32:47], v[192:195], v[164:167], v[32:47]
	v_mfma_f32_32x32x16_bf16 v[16:31], v[188:191], v[168:171], v[16:31]
	v_mfma_f32_32x32x16_bf16 v[0:15], v[192:195], v[168:171], v[0:15]
	s_waitcnt lgkmcnt(0)
	s_waitcnt vmcnt(0)
	s_barrier
; DI unsigned pack2(float a, float b) { f2_t f = {a, b}; bf2_t r = __builtin_convertvector(f, bf2_t); return __builtin_bit_cast(unsigned, r); }
; template <class AL, class BL, class EP>
; DI void gemm_tile256(AL al, BL bl, EP ep, int K, char* smem) {
;     ...
;     for (int i = 0; i < 4; ++i)
; #pragma unroll
;       for (int j = 0; j < 2; ++j)
; #pragma unroll
;         for (int g = 0; g < 4; ++g) {
;           u32x2 v = {pack2(acc[i][j][4 * g], acc[i][j][4 * g + 1]), pack2(acc[i][j][4 * g + 2], acc[i][j][4 * g + 3])};
;           *(u32x2*)(sCb + (128 * wm + 32 * i + r) * BLD + 64 * wn + 32 * j + 8 * g + 4 * h) = v;
	s_waitcnt lgkmcnt(0)
	v_mfma_f32_32x32x16_bf16 v[112:127], v[200:203], v[172:175], v[112:127]
	ds_read_b128 v[188:191], v198 offset:32768
	ds_read_b128 v[156:159], v134 offset:32768
	v_mfma_f32_32x32x16_bf16 v[96:111], v[204:207], v[172:175], v[96:111]
	ds_read_b128 v[192:195], v198 offset:34816
	ds_read_b128 v[160:163], v134 offset:34816
	v_mfma_f32_32x32x16_bf16 v[80:95], v[200:203], v[176:179], v[80:95]
	ds_read_b128 v[164:167], v134 offset:36864
	ds_read_b128 v[168:171], v134 offset:38912
	v_mfma_f32_32x32x16_bf16 v[64:79], v[204:207], v[176:179], v[64:79]
	v_mfma_f32_32x32x16_bf16 v[48:63], v[200:203], v[180:183], v[48:63]
	v_mfma_f32_32x32x16_bf16 v[32:47], v[204:207], v[180:183], v[32:47]
	v_mfma_f32_32x32x16_bf16 v[16:31], v[200:203], v[184:187], v[16:31]
	v_mfma_f32_32x32x16_bf16 v[0:15], v[204:207], v[184:187], v[0:15]
	s_waitcnt lgkmcnt(0)
	v_mfma_f32_32x32x16_bf16 v[112:127], v[188:191], v[156:159], v[112:127]
	ds_read_b128 v[200:203], v199 offset:32768
	ds_read_b128 v[172:175], v155 offset:32768
	v_mfma_f32_32x32x16_bf16 v[96:111], v[192:195], v[156:159], v[96:111]
	ds_read_b128 v[204:207], v199 offset:34816
	ds_read_b128 v[176:179], v155 offset:34816
	v_mfma_f32_32x32x16_bf16 v[80:95], v[188:191], v[160:163], v[80:95]
	ds_read_b128 v[180:183], v155 offset:36864
	ds_read_b128 v[184:187], v155 offset:38912
	v_mfma_f32_32x32x16_bf16 v[64:79], v[192:195], v[160:163], v[64:79]
	v_mfma_f32_32x32x16_bf16 v[48:63], v[188:191], v[164:167], v[48:63]
	v_mfma_f32_32x32x16_bf16 v[32:47], v[192:195], v[164:167], v[32:47]
	v_mfma_f32_32x32x16_bf16 v[16:31], v[188:191], v[168:171], v[16:31]
	v_mfma_f32_32x32x16_bf16 v[0:15], v[192:195], v[168:171], v[0:15]
	s_waitcnt lgkmcnt(0)
	s_waitcnt lgkmcnt(0)
	v_mfma_f32_32x32x16_bf16 v[112:127], v[200:203], v[172:175], v[112:127]
	v_mfma_f32_32x32x16_bf16 v[96:111], v[204:207], v[172:175], v[96:111]
	v_mfma_f32_32x32x16_bf16 v[80:95], v[200:203], v[176:179], v[80:95]
	v_mfma_f32_32x32x16_bf16 v[64:79], v[204:207], v[176:179], v[64:79]
	v_mfma_f32_32x32x16_bf16 v[48:63], v[200:203], v[180:183], v[48:63]
	v_mfma_f32_32x32x16_bf16 v[32:47], v[204:207], v[180:183], v[32:47]
	v_mfma_f32_32x32x16_bf16 v[16:31], v[200:203], v[184:187], v[16:31]
	v_mfma_f32_32x32x16_bf16 v[0:15], v[204:207], v[184:187], v[0:15]
	s_nop 15
	s_nop 3
	s_waitcnt lgkmcnt(4)
	v_lshl_or_b32 v128, v135, 7, v154
	v_mad_u64_u32 v[132:133], s[0:1], v153, s21, v[128:129]
	s_waitcnt lgkmcnt(0)
	s_barrier
; DI unsigned pack2(float a, float b) { f2_t f = {a, b}; bf2_t r = __builtin_convertvector(f, bf2_t); return __builtin_bit_cast(unsigned, r); }
; DI int tid512() { int t = threadIdx_x_raw(); asm volatile("" : "+v"(t)); return t; }
; template <class AL, class BL, class EP>
; DI void gemm_tile256(AL al, BL bl, EP ep, int K, char* smem) {
;     ...
;     for (int i = 0; i < 4; ++i)
; #pragma unroll
;       for (int j = 0; j < 2; ++j)
; #pragma unroll
;         for (int g = 0; g < 4; ++g) {
;           u32x2 v = {pack2(acc[i][j][4 * g], acc[i][j][4 * g + 1]), pack2(acc[i][j][4 * g + 2], acc[i][j][4 * g + 3])};
;           *(u32x2*)(sCb + (128 * wm + 32 * i + r) * BLD + 64 * wn + 32 * j + 8 * g + 4 * h) = v;
;         }
;     __syncthreads();
;   DI void operator()(const bf16_t* sCb) const {
;     const int t = tid512(), hf = (t >> 3) & 1, c8 = (t & 7) * 8;
;     const int cb = c0 + 64 * hf;
;     const bf16_t* base = sCb + 128 * hf;
;     float w0[8], w1[8], w2[8];
;     ld8f(conv + cb + c8, w0); ld8f(conv + DFF + cb + c8, w1); ld8f(conv + 2 * DFF + cb + c8, w2);
;     for (int rr = t >> 4; rr < 254; rr += 32) {
	v_lshlrev_b32_e32 v131, 7, v131
	v_bfe_u32 v200, v196, 3, 1
	v_lshlrev_b32_e32 v200, 6, v200
	v_or_b32_e32 v200, v200, v131
	v_ashrrev_i32_e32 v201, 31, v200
	v_lshlrev_b64 v[200:201], 2, v[200:201]
	v_lshlrev_b32_e32 v202, 3, v196
	v_and_b32_e32 v202, 56, v202
	v_lshlrev_b32_e32 v202, 2, v202
	v_mov_b32_e32 v203, 0
	v_lshl_add_u64 v[204:205], s[6:7], 0, v[200:201]
	v_lshl_add_u64 v[204:205], v[204:205], 0, v[202:203]
	v_lshl_add_u64 v[206:207], s[4:5], 0, v[200:201]
	v_lshl_add_u64 v[206:207], v[206:207], 0, v[202:203]
	v_lshl_add_u64 v[240:241], s[86:87], 0, v[200:201]
	v_lshl_add_u64 v[240:241], v[240:241], 0, v[202:203]
	global_load_dwordx4 v[208:211], v[204:205], off
	global_load_dwordx4 v[212:215], v[204:205], off offset:16
	global_load_dwordx4 v[216:219], v[206:207], off
	global_load_dwordx4 v[220:223], v[206:207], off offset:16
	global_load_dwordx4 v[224:227], v[240:241], off
	global_load_dwordx4 v[228:231], v[240:241], off offset:16
	s_nop 5
	v_cvt_pk_bf16_f32 v112, v112, v113
	v_cvt_pk_bf16_f32 v113, v114, v115
	v_cvt_pk_bf16_f32 v114, v116, v117
	v_cvt_pk_bf16_f32 v115, v118, v119
	ds_write2_b64 v132, v[112:113], v[114:115] offset1:2
	v_cvt_pk_bf16_f32 v112, v120, v121
	v_cvt_pk_bf16_f32 v113, v122, v123
	v_cvt_pk_bf16_f32 v96, v96, v97
	v_cvt_pk_bf16_f32 v97, v98, v99
	v_cvt_pk_bf16_f32 v98, v100, v101
	v_cvt_pk_bf16_f32 v99, v102, v103
	v_cvt_pk_bf16_f32 v114, v124, v125
	v_cvt_pk_bf16_f32 v115, v126, v127
	ds_write2_b64 v132, v[96:97], v[98:99] offset0:8 offset1:10
	s_nop 3
	v_cvt_pk_bf16_f32 v80, v80, v81
	v_cvt_pk_bf16_f32 v81, v82, v83
	v_cvt_pk_bf16_f32 v82, v84, v85
	v_cvt_pk_bf16_f32 v83, v86, v87
	v_add_u32_e32 v84, 0x4000, v132
	v_cvt_pk_bf16_f32 v96, v104, v105
	v_cvt_pk_bf16_f32 v97, v106, v107
	v_cvt_pk_bf16_f32 v64, v64, v65
	v_cvt_pk_bf16_f32 v65, v66, v67
	v_cvt_pk_bf16_f32 v66, v68, v69
	v_cvt_pk_bf16_f32 v67, v70, v71
	v_cvt_pk_bf16_f32 v98, v108, v109
	v_cvt_pk_bf16_f32 v99, v110, v111
	ds_write2_b64 v84, v[80:81], v[82:83] offset0:64 offset1:66
	s_nop 3
	v_cvt_pk_bf16_f32 v48, v48, v49
	v_cvt_pk_bf16_f32 v49, v50, v51
	v_cvt_pk_bf16_f32 v50, v52, v53
	v_cvt_pk_bf16_f32 v51, v54, v55
	v_add_u32_e32 v52, 0x8000, v132
	v_cvt_pk_bf16_f32 v80, v88, v89
	v_cvt_pk_bf16_f32 v81, v90, v91
	v_cvt_pk_bf16_f32 v32, v32, v33
	v_cvt_pk_bf16_f32 v33, v34, v35
	v_cvt_pk_bf16_f32 v34, v36, v37
	v_cvt_pk_bf16_f32 v35, v38, v39
	v_cvt_pk_bf16_f32 v82, v92, v93
	v_cvt_pk_bf16_f32 v83, v94, v95
	ds_write2_b64 v84, v[64:65], v[66:67] offset0:72 offset1:74
	s_nop 3
	v_cvt_pk_bf16_f32 v16, v16, v17
	v_cvt_pk_bf16_f32 v17, v18, v19
	v_cvt_pk_bf16_f32 v18, v20, v21
	v_cvt_pk_bf16_f32 v19, v22, v23
	v_add_u32_e32 v20, 0xc000, v132
	v_cvt_pk_bf16_f32 v64, v72, v73
	v_cvt_pk_bf16_f32 v65, v74, v75
	s_nop 0
	v_cvt_pk_bf16_f32 v0, v0, v1
	v_cvt_pk_bf16_f32 v1, v2, v3
	v_cvt_pk_bf16_f32 v2, v4, v5
	v_cvt_pk_bf16_f32 v3, v6, v7
	v_cvt_pk_bf16_f32 v66, v76, v77
	v_cvt_pk_bf16_f32 v67, v78, v79
	ds_write2_b64 v52, v[48:49], v[50:51] offset0:128 offset1:130
	v_cvt_pk_bf16_f32 v48, v56, v57
	v_cvt_pk_bf16_f32 v49, v58, v59
	v_cvt_pk_bf16_f32 v50, v60, v61
	v_cvt_pk_bf16_f32 v51, v62, v63
	ds_write2_b64 v52, v[32:33], v[34:35] offset0:136 offset1:138
	v_cvt_pk_bf16_f32 v32, v40, v41
	v_cvt_pk_bf16_f32 v33, v42, v43
	v_cvt_pk_bf16_f32 v34, v44, v45
	v_cvt_pk_bf16_f32 v35, v46, v47
	ds_write2_b64 v20, v[16:17], v[18:19] offset0:192 offset1:194
	v_cvt_pk_bf16_f32 v16, v24, v25
	v_cvt_pk_bf16_f32 v17, v26, v27
	v_cvt_pk_bf16_f32 v18, v28, v29
	v_cvt_pk_bf16_f32 v19, v30, v31
	ds_write2_b64 v20, v[0:1], v[2:3] offset0:200 offset1:202
	v_cvt_pk_bf16_f32 v0, v8, v9
	v_cvt_pk_bf16_f32 v1, v10, v11
	v_cvt_pk_bf16_f32 v2, v12, v13
	v_cvt_pk_bf16_f32 v3, v14, v15
	v_mov_b32_e32 v29, v196
	ds_write2_b64 v132, v[112:113], v[114:115] offset0:4 offset1:6
	ds_write2_b64 v132, v[96:97], v[98:99] offset0:12 offset1:14
	ds_write2_b64 v84, v[80:81], v[82:83] offset0:68 offset1:70
	ds_write2_b64 v84, v[64:65], v[66:67] offset0:76 offset1:78
	ds_write2_b64 v52, v[48:49], v[50:51] offset0:132 offset1:134
	ds_write2_b64 v52, v[32:33], v[34:35] offset0:140 offset1:142
	ds_write2_b64 v20, v[16:17], v[18:19] offset0:196 offset1:198
	ds_write2_b64 v20, v[0:1], v[2:3] offset0:204 offset1:206
	s_waitcnt lgkmcnt(0)
	s_barrier
	s_nop 0
	v_bfe_u32 v0, v29, 3, 1
	v_lshlrev_b32_e32 v30, 6, v0
	v_lshlrev_b32_e32 v1, 3, v29
	v_or_b32_e32 v24, v30, v131
	v_ashrrev_i32_e32 v26, 4, v29
	v_and_b32_e32 v27, 56, v1
	v_lshlrev_b32_e32 v28, 8, v0
	v_ashrrev_i32_e32 v25, 31, v24
	v_cmp_gt_i32_e32 vcc, s23, v26
	s_and_saveexec_b64 s[0:1], vcc
	s_cbranch_execz .LBB0_545
	v_lshlrev_b64 v[16:17], 2, v[24:25]
	v_lshl_add_u64 v[0:1], s[6:7], 0, v[16:17]
	v_lshlrev_b32_e32 v128, 2, v27
	v_lshl_add_u64 v[8:9], s[4:5], 0, v[16:17]
	v_lshl_add_u64 v[16:17], s[86:87], 0, v[16:17]
	v_lshl_add_u64 v[4:5], v[0:1], 0, v[128:129]
	v_lshl_add_u64 v[12:13], v[8:9], 0, v[128:129]
	v_lshl_add_u64 v[20:21], v[16:17], 0, v[128:129]
	s_waitcnt vmcnt(0)
	v_mov_b32_e32 v0, v208
	v_mov_b32_e32 v1, v209
	v_mov_b32_e32 v2, v210
	v_mov_b32_e32 v3, v211
	v_mov_b32_e32 v4, v212
	v_mov_b32_e32 v5, v213
	v_mov_b32_e32 v6, v214
	v_mov_b32_e32 v7, v215
	v_mov_b32_e32 v8, v216
	v_mov_b32_e32 v9, v217
	v_mov_b32_e32 v10, v218
	v_mov_b32_e32 v11, v219
	v_mov_b32_e32 v12, v220
	v_mov_b32_e32 v13, v221
	v_mov_b32_e32 v14, v222
	v_mov_b32_e32 v15, v223
	v_mov_b32_e32 v16, v224
	v_mov_b32_e32 v17, v225
	v_mov_b32_e32 v18, v226
	v_mov_b32_e32 v19, v227
	v_mov_b32_e32 v20, v228
	v_mov_b32_e32 v21, v229
	v_mov_b32_e32 v22, v230
	v_mov_b32_e32 v23, v231
	v_lshlrev_b32_e32 v33, 4, v29
	v_mad_i64_i32 v[34:35], s[14:15], v26, s24, 0
	v_mul_lo_u32 v31, v26, s21
	v_and_b32_e32 v36, 0x70, v33
	v_mad_i64_i32 v[34:35], s[14:15], v130, s25, v[34:35]
	v_add_u32_e32 v30, v131, v30
	v_add3_u32 v33, v31, v28, v36
	v_or_b32_e32 v34, v34, v36
	v_ashrrev_i32_e32 v31, 31, v30
	v_readlane_b32 s10, v246, 51
	v_lshl_add_u64 v[30:31], v[30:31], 1, v[34:35]
	v_readlane_b32 s11, v246, 52
	v_subrev_u32_e32 v32, 32, v26
	s_mov_b64 s[14:15], 0
	v_lshl_add_u64 v[30:31], s[10:11], 0, v[30:31]
	s_waitcnt vmcnt(0)

; DI int tid512() { int t = threadIdx_x_raw(); asm volatile("" : "+v"(t)); return t; }
;   DI void operator()(bf16_t* sCb) const {
;     ...
;       if (nat) {
;         for (int id = tid512(); id < 4096; id += 512) {
;           int row = id >> 4, c8 = (id & 15) * 8;
;           *(u32x4*)(nat + (size_t)(m0 + row) * ldn + coff + c8) = *(const u32x4*)(base + row * BLD + c8);
;         }
;       }
.LBB0_789:
	v_mov_b32_e32 v0, v196
	s_nop 0
	v_cmp_gt_i32_e32 vcc, s50, v0
	s_and_saveexec_b64 s[34:35], vcc
	s_cbranch_execz .LBB0_792
	s_ashr_i32 s29, s28, 31
	s_lshl_b64 s[28:29], s[28:29], 1
	s_add_u32 s28, s30, s28
	s_addc_u32 s29, s31, s29
	v_lshlrev_b32_e32 v1, 3, v0
	s_mov_b64 s[30:31], 0
	v_ashrrev_i32_e32 v2, 4, v0
	v_lshlrev_b32_e32 v3, 1, v1
	v_mul_lo_u32 v5, v2, s46
	v_and_b32_e32 v128, 0xf0, v3
	v_add3_u32 v3, s58, v5, v128
	v_add_u32_e32 v10, 0x10800, v3
	ds_read_b128 v[64:67], v3
	ds_read_b128 v[68:71], v3 offset:16896
	ds_read_b128 v[72:75], v3 offset:33792
	ds_read_b128 v[76:79], v3 offset:50688
	ds_read_b128 v[80:83], v10
	ds_read_b128 v[84:87], v10 offset:16896
	ds_read_b128 v[88:91], v10 offset:33792
	ds_read_b128 v[92:95], v10 offset:50688
	v_ashrrev_i32_e32 v2, 4, v0
	v_add_u32_e32 v2, s52, v2
	v_ashrrev_i32_e32 v8, 31, v2
	v_mul_lo_u32 v9, s27, v2
	v_mad_u64_u32 v[6:7], s[60:61], s26, v2, 0
	v_mul_lo_u32 v8, s26, v8
	v_add3_u32 v7, v7, v8, v9
	v_lshl_add_u64 v[6:7], v[6:7], 1, s[28:29]
	v_lshl_add_u64 v[6:7], v[6:7], 0, v[128:129]
	s_waitcnt lgkmcnt(7)
	global_store_dwordx4 v[6:7], v[64:67], off
	v_add_u32_e32 v0, 0x200, v0
	v_ashrrev_i32_e32 v2, 4, v0
	v_add_u32_e32 v2, s52, v2
	v_ashrrev_i32_e32 v8, 31, v2
	v_mul_lo_u32 v9, s27, v2
	v_mad_u64_u32 v[6:7], s[60:61], s26, v2, 0
	v_mul_lo_u32 v8, s26, v8
	v_add3_u32 v7, v7, v8, v9
	v_lshl_add_u64 v[6:7], v[6:7], 1, s[28:29]
	v_lshl_add_u64 v[6:7], v[6:7], 0, v[128:129]
	s_waitcnt lgkmcnt(6)
	global_store_dwordx4 v[6:7], v[68:71], off
	v_add_u32_e32 v0, 0x200, v0
	v_ashrrev_i32_e32 v2, 4, v0
	v_add_u32_e32 v2, s52, v2
	v_ashrrev_i32_e32 v8, 31, v2
	v_mul_lo_u32 v9, s27, v2
	v_mad_u64_u32 v[6:7], s[60:61], s26, v2, 0
	v_mul_lo_u32 v8, s26, v8
	v_add3_u32 v7, v7, v8, v9
	v_lshl_add_u64 v[6:7], v[6:7], 1, s[28:29]
	v_lshl_add_u64 v[6:7], v[6:7], 0, v[128:129]
	s_waitcnt lgkmcnt(5)
	global_store_dwordx4 v[6:7], v[72:75], off
	v_add_u32_e32 v0, 0x200, v0
	v_ashrrev_i32_e32 v2, 4, v0
	v_add_u32_e32 v2, s52, v2
	v_ashrrev_i32_e32 v8, 31, v2
	v_mul_lo_u32 v9, s27, v2
	v_mad_u64_u32 v[6:7], s[60:61], s26, v2, 0
	v_mul_lo_u32 v8, s26, v8
	v_add3_u32 v7, v7, v8, v9
	v_lshl_add_u64 v[6:7], v[6:7], 1, s[28:29]
	v_lshl_add_u64 v[6:7], v[6:7], 0, v[128:129]
	s_waitcnt lgkmcnt(4)
	global_store_dwordx4 v[6:7], v[76:79], off
	v_add_u32_e32 v0, 0x200, v0
	v_ashrrev_i32_e32 v2, 4, v0
	v_add_u32_e32 v2, s52, v2
	v_ashrrev_i32_e32 v8, 31, v2
	v_mul_lo_u32 v9, s27, v2
	v_mad_u64_u32 v[6:7], s[60:61], s26, v2, 0
	v_mul_lo_u32 v8, s26, v8
	v_add3_u32 v7, v7, v8, v9
	v_lshl_add_u64 v[6:7], v[6:7], 1, s[28:29]
	v_lshl_add_u64 v[6:7], v[6:7], 0, v[128:129]
	s_waitcnt lgkmcnt(3)
	global_store_dwordx4 v[6:7], v[80:83], off
	v_add_u32_e32 v0, 0x200, v0
	v_ashrrev_i32_e32 v2, 4, v0
	v_add_u32_e32 v2, s52, v2
	v_ashrrev_i32_e32 v8, 31, v2
	v_mul_lo_u32 v9, s27, v2
	v_mad_u64_u32 v[6:7], s[60:61], s26, v2, 0
	v_mul_lo_u32 v8, s26, v8
	v_add3_u32 v7, v7, v8, v9
	v_lshl_add_u64 v[6:7], v[6:7], 1, s[28:29]
	v_lshl_add_u64 v[6:7], v[6:7], 0, v[128:129]
	s_waitcnt lgkmcnt(2)
	global_store_dwordx4 v[6:7], v[84:87], off
	v_add_u32_e32 v0, 0x200, v0
	v_ashrrev_i32_e32 v2, 4, v0
	v_add_u32_e32 v2, s52, v2
	v_ashrrev_i32_e32 v8, 31, v2
	v_mul_lo_u32 v9, s27, v2
	v_mad_u64_u32 v[6:7], s[60:61], s26, v2, 0
	v_mul_lo_u32 v8, s26, v8
	v_add3_u32 v7, v7, v8, v9
	v_lshl_add_u64 v[6:7], v[6:7], 1, s[28:29]
	v_lshl_add_u64 v[6:7], v[6:7], 0, v[128:129]
	s_waitcnt lgkmcnt(1)
	global_store_dwordx4 v[6:7], v[88:91], off
	v_add_u32_e32 v0, 0x200, v0
	v_ashrrev_i32_e32 v2, 4, v0
	v_add_u32_e32 v2, s52, v2
	v_ashrrev_i32_e32 v8, 31, v2
	v_mul_lo_u32 v9, s27, v2
	v_mad_u64_u32 v[6:7], s[60:61], s26, v2, 0
	v_mul_lo_u32 v8, s26, v8
	v_add3_u32 v7, v7, v8, v9
	v_lshl_add_u64 v[6:7], v[6:7], 1, s[28:29]
	v_lshl_add_u64 v[6:7], v[6:7], 0, v[128:129]
	s_waitcnt lgkmcnt(0)
	global_store_dwordx4 v[6:7], v[92:95], off

; #define G_LOADA(kt_) { _Pragma("unroll") for (int i = 0; i < 4; ++i) ra[i] = al(lrow + 64 * i, (kt_) * 64 + lck * 8); }
; #define G_LOADB(kt_) { _Pragma("unroll") for (int i = 0; i < 4; ++i) rb[i] = bl(lrow + 64 * i, (kt_) * 64 + lck * 8); }
; #define G_STOREA(buf_) { bf16_t* nA = sA + (buf_) * 256 * GLD; _Pragma("unroll") for (int i = 0; i < 4; ++i) *(u32x4*)(nA + (lrow + 64 * i) * GLD + lck * 8) = ra[i]; }
; #define G_STOREB(buf_) { bf16_t* nB = sB + (buf_) * 256 * GLD; _Pragma("unroll") for (int i = 0; i < 4; ++i) *(u32x4*)(nB + (lrow + 64 * i) * GLD + lck * 8) = rb[i]; }
; template <class AL, class BL, class EP>
; DI void gemm_tile256(AL al, BL bl, EP ep, int K, char* smem) {
;     ...
;   const int KT = K >> 6;
;     ...
;   G_LOADA(0); G_LOADB(0);
;   __syncthreads();
;   G_STOREA(0); G_STOREB(0);
;   if (KT > 1) G_LOADB(1);
;   __syncthreads();
;   for (int kt = 0; kt < KT; kt += 2) {
;     G_STEP(0, kt);
;     if (kt + 1 >= KT) break;
;     G_STEP(1, kt + 1);
;   }
.Lgk_ph15_loop:
	s_waitcnt lgkmcnt(0)
	v_mfma_f32_32x32x16_bf16 v[112:127], v[188:191], v[156:159], v[112:127]
	ds_read_b128 v[200:203], v199
	ds_read_b128 v[172:175], v155
	v_mfma_f32_32x32x16_bf16 v[96:111], v[192:195], v[156:159], v[96:111]
	ds_read_b128 v[204:207], v199 offset:2048
	ds_read_b128 v[176:179], v155 offset:2048
	v_mfma_f32_32x32x16_bf16 v[80:95], v[188:191], v[160:163], v[80:95]
	ds_read_b128 v[180:183], v155 offset:4096
	ds_read_b128 v[184:187], v155 offset:6144
	v_mfma_f32_32x32x16_bf16 v[64:79], v[192:195], v[160:163], v[64:79]
	s_add_u32 m0, s32, 0x22000
	s_nop 0
	global_load_lds_dwordx4 v[218:219], off
	v_lshl_add_u64 v[218:219], v[218:219], 0, s[10:11]
	v_mfma_f32_32x32x16_bf16 v[48:63], v[188:191], v[164:167], v[48:63]
	v_mfma_f32_32x32x16_bf16 v[32:47], v[192:195], v[164:167], v[32:47]
	v_mfma_f32_32x32x16_bf16 v[16:31], v[188:191], v[168:171], v[16:31]
	v_mfma_f32_32x32x16_bf16 v[0:15], v[192:195], v[168:171], v[0:15]
	s_add_u32 m0, s32, 0x26000
	s_nop 0
	global_load_lds_dwordx4 v[222:223], off
	v_lshl_add_u64 v[222:223], v[222:223], 0, s[10:11]
	s_waitcnt lgkmcnt(0)
	s_waitcnt vmcnt(12)
	s_barrier
	s_waitcnt lgkmcnt(0)
	v_mfma_f32_32x32x16_bf16 v[112:127], v[200:203], v[172:175], v[112:127]
	ds_read_b128 v[188:191], v198 offset:32768
	ds_read_b128 v[156:159], v134 offset:32768
	v_mfma_f32_32x32x16_bf16 v[96:111], v[204:207], v[172:175], v[96:111]
	ds_read_b128 v[192:195], v198 offset:34816
	ds_read_b128 v[160:163], v134 offset:34816
	v_mfma_f32_32x32x16_bf16 v[80:95], v[200:203], v[176:179], v[80:95]
	ds_read_b128 v[164:167], v134 offset:36864
	ds_read_b128 v[168:171], v134 offset:38912
	v_mfma_f32_32x32x16_bf16 v[64:79], v[204:207], v[176:179], v[64:79]
	s_add_u32 m0, s32, 0x0
	s_nop 0
	global_load_lds_dwordx4 v[216:217], off
	v_lshl_add_u64 v[216:217], v[216:217], 0, s[10:11]
	v_mfma_f32_32x32x16_bf16 v[48:63], v[200:203], v[180:183], v[48:63]
	v_mfma_f32_32x32x16_bf16 v[32:47], v[204:207], v[180:183], v[32:47]
	v_mfma_f32_32x32x16_bf16 v[16:31], v[200:203], v[184:187], v[16:31]
	v_mfma_f32_32x32x16_bf16 v[0:15], v[204:207], v[184:187], v[0:15]
	s_add_u32 m0, s32, 0x4000
	s_nop 0
	global_load_lds_dwordx4 v[220:221], off
	v_lshl_add_u64 v[220:221], v[220:221], 0, s[10:11]
	s_waitcnt lgkmcnt(0)
	v_mfma_f32_32x32x16_bf16 v[112:127], v[188:191], v[156:159], v[112:127]
	ds_read_b128 v[200:203], v199 offset:32768
	ds_read_b128 v[172:175], v155 offset:32768
	v_mfma_f32_32x32x16_bf16 v[96:111], v[192:195], v[156:159], v[96:111]
	ds_read_b128 v[204:207], v199 offset:34816
	ds_read_b128 v[176:179], v155 offset:34816
	v_mfma_f32_32x32x16_bf16 v[80:95], v[188:191], v[160:163], v[80:95]
	ds_read_b128 v[180:183], v155 offset:36864
	ds_read_b128 v[184:187], v155 offset:38912
	v_mfma_f32_32x32x16_bf16 v[64:79], v[192:195], v[160:163], v[64:79]
	s_add_u32 m0, s32, 0x2000
	s_nop 0
	global_load_lds_dwordx4 v[218:219], off
	v_lshl_add_u64 v[218:219], v[218:219], 0, s[10:11]
	v_mfma_f32_32x32x16_bf16 v[48:63], v[188:191], v[164:167], v[48:63]
	v_mfma_f32_32x32x16_bf16 v[32:47], v[192:195], v[164:167], v[32:47]
	v_mfma_f32_32x32x16_bf16 v[16:31], v[188:191], v[168:171], v[16:31]
	v_mfma_f32_32x32x16_bf16 v[0:15], v[192:195], v[168:171], v[0:15]
	s_add_u32 m0, s32, 0x6000
	s_nop 0
	global_load_lds_dwordx4 v[222:223], off
	v_lshl_add_u64 v[222:223], v[222:223], 0, s[10:11]
	s_waitcnt lgkmcnt(0)
	s_waitcnt vmcnt(12)
	s_barrier
	s_waitcnt lgkmcnt(0)
	v_mfma_f32_32x32x16_bf16 v[112:127], v[200:203], v[172:175], v[112:127]
	ds_read_b128 v[188:191], v210
	ds_read_b128 v[156:159], v208
	v_mfma_f32_32x32x16_bf16 v[96:111], v[204:207], v[172:175], v[96:111]
	ds_read_b128 v[192:195], v210 offset:2048
	ds_read_b128 v[160:163], v208 offset:2048
	v_mfma_f32_32x32x16_bf16 v[80:95], v[200:203], v[176:179], v[80:95]
	ds_read_b128 v[164:167], v208 offset:4096
	ds_read_b128 v[168:171], v208 offset:6144
	v_mfma_f32_32x32x16_bf16 v[64:79], v[204:207], v[176:179], v[64:79]
	s_add_u32 m0, s32, 0x8000
	s_nop 0
	global_load_lds_dwordx4 v[216:217], off
	v_lshl_add_u64 v[216:217], v[216:217], 0, s[10:11]
	v_mfma_f32_32x32x16_bf16 v[48:63], v[200:203], v[180:183], v[48:63]
	v_mfma_f32_32x32x16_bf16 v[32:47], v[204:207], v[180:183], v[32:47]
	v_mfma_f32_32x32x16_bf16 v[16:31], v[200:203], v[184:187], v[16:31]
	v_mfma_f32_32x32x16_bf16 v[0:15], v[204:207], v[184:187], v[0:15]
	s_add_u32 m0, s32, 0xc000
	s_nop 0
	global_load_lds_dwordx4 v[220:221], off
	v_lshl_add_u64 v[220:221], v[220:221], 0, s[10:11]
	s_waitcnt lgkmcnt(0)
	v_mfma_f32_32x32x16_bf16 v[112:127], v[188:191], v[156:159], v[112:127]
	ds_read_b128 v[200:203], v211
	ds_read_b128 v[172:175], v209
	v_mfma_f32_32x32x16_bf16 v[96:111], v[192:195], v[156:159], v[96:111]
	ds_read_b128 v[204:207], v211 offset:2048
	ds_read_b128 v[176:179], v209 offset:2048
	v_mfma_f32_32x32x16_bf16 v[80:95], v[188:191], v[160:163], v[80:95]
	ds_read_b128 v[180:183], v209 offset:4096
	ds_read_b128 v[184:187], v209 offset:6144
	v_mfma_f32_32x32x16_bf16 v[64:79], v[192:195], v[160:163], v[64:79]
	s_add_u32 m0, s32, 0xa000
	s_nop 0
	global_load_lds_dwordx4 v[218:219], off
	v_lshl_add_u64 v[218:219], v[218:219], 0, s[10:11]
	v_mfma_f32_32x32x16_bf16 v[48:63], v[188:191], v[164:167], v[48:63]
	v_mfma_f32_32x32x16_bf16 v[32:47], v[192:195], v[164:167], v[32:47]
	v_mfma_f32_32x32x16_bf16 v[16:31], v[188:191], v[168:171], v[16:31]
	v_mfma_f32_32x32x16_bf16 v[0:15], v[192:195], v[168:171], v[0:15]
	s_add_u32 m0, s32, 0xe000
	s_nop 0
	global_load_lds_dwordx4 v[222:223], off
	v_lshl_add_u64 v[222:223], v[222:223], 0, s[10:11]
	s_waitcnt lgkmcnt(0)
	s_waitcnt vmcnt(12)
	s_barrier
; #define G_LOADA(kt_) { _Pragma("unroll") for (int i = 0; i < 4; ++i) ra[i] = al(lrow + 64 * i, (kt_) * 64 + lck * 8); }
; #define G_LOADB(kt_) { _Pragma("unroll") for (int i = 0; i < 4; ++i) rb[i] = bl(lrow + 64 * i, (kt_) * 64 + lck * 8); }
; #define G_STOREA(buf_) { bf16_t* nA = sA + (buf_) * 256 * GLD; _Pragma("unroll") for (int i = 0; i < 4; ++i) *(u32x4*)(nA + (lrow + 64 * i) * GLD + lck * 8) = ra[i]; }
; #define G_STOREB(buf_) { bf16_t* nB = sB + (buf_) * 256 * GLD; _Pragma("unroll") for (int i = 0; i < 4; ++i) *(u32x4*)(nB + (lrow + 64 * i) * GLD + lck * 8) = rb[i]; }
; template <class AL, class BL, class EP>
; DI void gemm_tile256(AL al, BL bl, EP ep, int K, char* smem) {
;     ...
;   G_LOADA(0); G_LOADB(0);
;   __syncthreads();
;   G_STOREA(0); G_STOREB(0);
;   if (KT > 1) G_LOADB(1);
;   __syncthreads();
;   for (int kt = 0; kt < KT; kt += 2) {
;     G_STEP(0, kt);
;     if (kt + 1 >= KT) break;
;     G_STEP(1, kt + 1);
;   }
	s_waitcnt lgkmcnt(0)
	v_mfma_f32_32x32x16_bf16 v[112:127], v[200:203], v[172:175], v[112:127]
	ds_read_b128 v[188:191], v210 offset:32768
	ds_read_b128 v[156:159], v208 offset:32768
	v_mfma_f32_32x32x16_bf16 v[96:111], v[204:207], v[172:175], v[96:111]
	ds_read_b128 v[192:195], v210 offset:34816
	ds_read_b128 v[160:163], v208 offset:34816
	v_mfma_f32_32x32x16_bf16 v[80:95], v[200:203], v[176:179], v[80:95]
	ds_read_b128 v[164:167], v208 offset:36864
	ds_read_b128 v[168:171], v208 offset:38912
	v_mfma_f32_32x32x16_bf16 v[64:79], v[204:207], v[176:179], v[64:79]
	s_add_u32 m0, s32, 0x10000
	s_nop 0
	global_load_lds_dwordx4 v[216:217], off
	v_lshl_add_u64 v[216:217], v[216:217], 0, s[10:11]
	v_mfma_f32_32x32x16_bf16 v[48:63], v[200:203], v[180:183], v[48:63]
	v_mfma_f32_32x32x16_bf16 v[32:47], v[204:207], v[180:183], v[32:47]
	v_mfma_f32_32x32x16_bf16 v[16:31], v[200:203], v[184:187], v[16:31]
	v_mfma_f32_32x32x16_bf16 v[0:15], v[204:207], v[184:187], v[0:15]
	s_add_u32 m0, s32, 0x14000
	s_nop 0
	global_load_lds_dwordx4 v[220:221], off
	v_lshl_add_u64 v[220:221], v[220:221], 0, s[10:11]
	s_waitcnt lgkmcnt(0)
	v_mfma_f32_32x32x16_bf16 v[112:127], v[188:191], v[156:159], v[112:127]
	ds_read_b128 v[200:203], v211 offset:32768
	ds_read_b128 v[172:175], v209 offset:32768
	v_mfma_f32_32x32x16_bf16 v[96:111], v[192:195], v[156:159], v[96:111]
	ds_read_b128 v[204:207], v211 offset:34816
	ds_read_b128 v[176:179], v209 offset:34816
	v_mfma_f32_32x32x16_bf16 v[80:95], v[188:191], v[160:163], v[80:95]
	ds_read_b128 v[180:183], v209 offset:36864
	ds_read_b128 v[184:187], v209 offset:38912
	v_mfma_f32_32x32x16_bf16 v[64:79], v[192:195], v[160:163], v[64:79]
	s_add_u32 m0, s32, 0x12000
	s_nop 0
	global_load_lds_dwordx4 v[218:219], off
	v_lshl_add_u64 v[218:219], v[218:219], 0, s[10:11]
	v_mfma_f32_32x32x16_bf16 v[48:63], v[188:191], v[164:167], v[48:63]
	v_mfma_f32_32x32x16_bf16 v[32:47], v[192:195], v[164:167], v[32:47]
	v_mfma_f32_32x32x16_bf16 v[16:31], v[188:191], v[168:171], v[16:31]
	v_mfma_f32_32x32x16_bf16 v[0:15], v[192:195], v[168:171], v[0:15]
	s_add_u32 m0, s32, 0x16000
	s_nop 0
	global_load_lds_dwordx4 v[222:223], off
	v_lshl_add_u64 v[222:223], v[222:223], 0, s[10:11]
	s_waitcnt lgkmcnt(0)
	s_waitcnt vmcnt(12)
	s_barrier
	s_waitcnt lgkmcnt(0)
	v_mfma_f32_32x32x16_bf16 v[112:127], v[200:203], v[172:175], v[112:127]
	ds_read_b128 v[188:191], v214
	ds_read_b128 v[156:159], v212
	v_mfma_f32_32x32x16_bf16 v[96:111], v[204:207], v[172:175], v[96:111]
	ds_read_b128 v[192:195], v214 offset:2048
	ds_read_b128 v[160:163], v212 offset:2048
	v_mfma_f32_32x32x16_bf16 v[80:95], v[200:203], v[176:179], v[80:95]
	ds_read_b128 v[164:167], v212 offset:4096
	ds_read_b128 v[168:171], v212 offset:6144
	v_mfma_f32_32x32x16_bf16 v[64:79], v[204:207], v[176:179], v[64:79]
	s_add_u32 m0, s32, 0x18000
	s_nop 0
	global_load_lds_dwordx4 v[216:217], off
	v_lshl_add_u64 v[216:217], v[216:217], 0, s[10:11]
	v_mfma_f32_32x32x16_bf16 v[48:63], v[200:203], v[180:183], v[48:63]
	v_mfma_f32_32x32x16_bf16 v[32:47], v[204:207], v[180:183], v[32:47]
	v_mfma_f32_32x32x16_bf16 v[16:31], v[200:203], v[184:187], v[16:31]
	v_mfma_f32_32x32x16_bf16 v[0:15], v[204:207], v[184:187], v[0:15]
	s_add_u32 m0, s32, 0x1c000
	s_nop 0
	global_load_lds_dwordx4 v[220:221], off
	v_lshl_add_u64 v[220:221], v[220:221], 0, s[10:11]
	s_waitcnt lgkmcnt(0)
	v_mfma_f32_32x32x16_bf16 v[112:127], v[188:191], v[156:159], v[112:127]
	ds_read_b128 v[200:203], v215
	ds_read_b128 v[172:175], v213
	v_mfma_f32_32x32x16_bf16 v[96:111], v[192:195], v[156:159], v[96:111]
	ds_read_b128 v[204:207], v215 offset:2048
	ds_read_b128 v[176:179], v213 offset:2048
	v_mfma_f32_32x32x16_bf16 v[80:95], v[188:191], v[160:163], v[80:95]
	ds_read_b128 v[180:183], v213 offset:4096
	ds_read_b128 v[184:187], v213 offset:6144
	v_mfma_f32_32x32x16_bf16 v[64:79], v[192:195], v[160:163], v[64:79]
	s_add_u32 m0, s32, 0x1a000
	s_nop 0
	global_load_lds_dwordx4 v[218:219], off
	v_lshl_add_u64 v[218:219], v[218:219], 0, s[10:11]
	v_mfma_f32_32x32x16_bf16 v[48:63], v[188:191], v[164:167], v[48:63]
	v_mfma_f32_32x32x16_bf16 v[32:47], v[192:195], v[164:167], v[32:47]
	v_mfma_f32_32x32x16_bf16 v[16:31], v[188:191], v[168:171], v[16:31]
	v_mfma_f32_32x32x16_bf16 v[0:15], v[192:195], v[168:171], v[0:15]
	s_add_u32 m0, s32, 0x1e000
	s_nop 0
	global_load_lds_dwordx4 v[222:223], off
	v_lshl_add_u64 v[222:223], v[222:223], 0, s[10:11]
	s_waitcnt lgkmcnt(0)
	s_waitcnt vmcnt(12)
	s_barrier
	s_waitcnt lgkmcnt(0)
	v_mfma_f32_32x32x16_bf16 v[112:127], v[200:203], v[172:175], v[112:127]
	ds_read_b128 v[188:191], v198
	ds_read_b128 v[156:159], v134
	v_mfma_f32_32x32x16_bf16 v[96:111], v[204:207], v[172:175], v[96:111]
	ds_read_b128 v[192:195], v198 offset:2048
	ds_read_b128 v[160:163], v134 offset:2048
	v_mfma_f32_32x32x16_bf16 v[80:95], v[200:203], v[176:179], v[80:95]
	ds_read_b128 v[164:167], v134 offset:4096
	ds_read_b128 v[168:171], v134 offset:6144
	v_mfma_f32_32x32x16_bf16 v[64:79], v[204:207], v[176:179], v[64:79]
	s_add_u32 m0, s32, 0x20000
	s_nop 0
	global_load_lds_dwordx4 v[216:217], off
	v_lshl_add_u64 v[216:217], v[216:217], 0, s[10:11]
	v_mfma_f32_32x32x16_bf16 v[48:63], v[200:203], v[180:183], v[48:63]
	v_mfma_f32_32x32x16_bf16 v[32:47], v[204:207], v[180:183], v[32:47]
	v_mfma_f32_32x32x16_bf16 v[16:31], v[200:203], v[184:187], v[16:31]
	v_mfma_f32_32x32x16_bf16 v[0:15], v[204:207], v[184:187], v[0:15]
	s_add_u32 m0, s32, 0x24000
	s_nop 0
	global_load_lds_dwordx4 v[220:221], off
	v_lshl_add_u64 v[220:221], v[220:221], 0, s[10:11]
	s_sub_u32 s33, s33, 1
	s_cmp_lg_u32 s33, 0
	s_cbranch_scc1 .Lgk_ph15_loop
; #define G_LOADA(kt_) { _Pragma("unroll") for (int i = 0; i < 4; ++i) ra[i] = al(lrow + 64 * i, (kt_) * 64 + lck * 8); }
; #define G_LOADB(kt_) { _Pragma("unroll") for (int i = 0; i < 4; ++i) rb[i] = bl(lrow + 64 * i, (kt_) * 64 + lck * 8); }
; #define G_STOREA(buf_) { bf16_t* nA = sA + (buf_) * 256 * GLD; _Pragma("unroll") for (int i = 0; i < 4; ++i) *(u32x4*)(nA + (lrow + 64 * i) * GLD + lck * 8) = ra[i]; }
; #define G_STOREB(buf_) { bf16_t* nB = sB + (buf_) * 256 * GLD; _Pragma("unroll") for (int i = 0; i < 4; ++i) *(u32x4*)(nB + (lrow + 64 * i) * GLD + lck * 8) = rb[i]; }
; template <class AL, class BL, class EP>
; DI void gemm_tile256(AL al, BL bl, EP ep, int K, char* smem) {
;     ...
;   G_LOADA(0); G_LOADB(0);
;   __syncthreads();
;   G_STOREA(0); G_STOREB(0);
;   if (KT > 1) G_LOADB(1);
;   __syncthreads();
;   for (int kt = 0; kt < KT; kt += 2) {
;     G_STEP(0, kt);
;     if (kt + 1 >= KT) break;
;     G_STEP(1, kt + 1);
;   }
	s_waitcnt lgkmcnt(0)
	v_mfma_f32_32x32x16_bf16 v[112:127], v[188:191], v[156:159], v[112:127]
	ds_read_b128 v[200:203], v199
	ds_read_b128 v[172:175], v155
	v_mfma_f32_32x32x16_bf16 v[96:111], v[192:195], v[156:159], v[96:111]
	ds_read_b128 v[204:207], v199 offset:2048
	ds_read_b128 v[176:179], v155 offset:2048
	v_mfma_f32_32x32x16_bf16 v[80:95], v[188:191], v[160:163], v[80:95]
	ds_read_b128 v[180:183], v155 offset:4096
	ds_read_b128 v[184:187], v155 offset:6144
	v_mfma_f32_32x32x16_bf16 v[64:79], v[192:195], v[160:163], v[64:79]
	s_add_u32 m0, s32, 0x22000
	s_nop 0
	global_load_lds_dwordx4 v[218:219], off
	v_lshl_add_u64 v[218:219], v[218:219], 0, s[10:11]
	v_mfma_f32_32x32x16_bf16 v[48:63], v[188:191], v[164:167], v[48:63]
	v_mfma_f32_32x32x16_bf16 v[32:47], v[192:195], v[164:167], v[32:47]
	v_mfma_f32_32x32x16_bf16 v[16:31], v[188:191], v[168:171], v[16:31]
	v_mfma_f32_32x32x16_bf16 v[0:15], v[192:195], v[168:171], v[0:15]
	s_add_u32 m0, s32, 0x26000
	s_nop 0
	global_load_lds_dwordx4 v[222:223], off
	v_lshl_add_u64 v[222:223], v[222:223], 0, s[10:11]
	s_waitcnt lgkmcnt(0)
	s_waitcnt vmcnt(12)
	s_barrier
	s_waitcnt lgkmcnt(0)
	v_mfma_f32_32x32x16_bf16 v[112:127], v[200:203], v[172:175], v[112:127]
	ds_read_b128 v[188:191], v198 offset:32768
	ds_read_b128 v[156:159], v134 offset:32768
	v_mfma_f32_32x32x16_bf16 v[96:111], v[204:207], v[172:175], v[96:111]
	ds_read_b128 v[192:195], v198 offset:34816
	ds_read_b128 v[160:163], v134 offset:34816
	v_mfma_f32_32x32x16_bf16 v[80:95], v[200:203], v[176:179], v[80:95]
	ds_read_b128 v[164:167], v134 offset:36864
	ds_read_b128 v[168:171], v134 offset:38912
	v_mfma_f32_32x32x16_bf16 v[64:79], v[204:207], v[176:179], v[64:79]
	s_add_u32 m0, s32, 0x0
	s_nop 0
	global_load_lds_dwordx4 v[216:217], off
	v_lshl_add_u64 v[216:217], v[216:217], 0, s[10:11]
	v_mfma_f32_32x32x16_bf16 v[48:63], v[200:203], v[180:183], v[48:63]
	v_mfma_f32_32x32x16_bf16 v[32:47], v[204:207], v[180:183], v[32:47]
	v_mfma_f32_32x32x16_bf16 v[16:31], v[200:203], v[184:187], v[16:31]
	v_mfma_f32_32x32x16_bf16 v[0:15], v[204:207], v[184:187], v[0:15]
	s_add_u32 m0, s32, 0x4000
	s_nop 0
	global_load_lds_dwordx4 v[220:221], off
	v_lshl_add_u64 v[220:221], v[220:221], 0, s[10:11]
	s_waitcnt lgkmcnt(0)
	v_mfma_f32_32x32x16_bf16 v[112:127], v[188:191], v[156:159], v[112:127]
	ds_read_b128 v[200:203], v199 offset:32768
	ds_read_b128 v[172:175], v155 offset:32768
	v_mfma_f32_32x32x16_bf16 v[96:111], v[192:195], v[156:159], v[96:111]
	ds_read_b128 v[204:207], v199 offset:34816
	ds_read_b128 v[176:179], v155 offset:34816
	v_mfma_f32_32x32x16_bf16 v[80:95], v[188:191], v[160:163], v[80:95]
	ds_read_b128 v[180:183], v155 offset:36864
	ds_read_b128 v[184:187], v155 offset:38912
	v_mfma_f32_32x32x16_bf16 v[64:79], v[192:195], v[160:163], v[64:79]
	s_add_u32 m0, s32, 0x2000
	s_nop 0
	global_load_lds_dwordx4 v[218:219], off
	v_lshl_add_u64 v[218:219], v[218:219], 0, s[10:11]
	v_mfma_f32_32x32x16_bf16 v[48:63], v[188:191], v[164:167], v[48:63]
	v_mfma_f32_32x32x16_bf16 v[32:47], v[192:195], v[164:167], v[32:47]
	v_mfma_f32_32x32x16_bf16 v[16:31], v[188:191], v[168:171], v[16:31]
	v_mfma_f32_32x32x16_bf16 v[0:15], v[192:195], v[168:171], v[0:15]
	s_add_u32 m0, s32, 0x6000
	s_nop 0
	global_load_lds_dwordx4 v[222:223], off
	v_lshl_add_u64 v[222:223], v[222:223], 0, s[10:11]
	s_waitcnt lgkmcnt(0)
	s_waitcnt vmcnt(12)
	s_barrier
	s_waitcnt lgkmcnt(0)
	v_mfma_f32_32x32x16_bf16 v[112:127], v[200:203], v[172:175], v[112:127]
	ds_read_b128 v[188:191], v210
	ds_read_b128 v[156:159], v208
	v_mfma_f32_32x32x16_bf16 v[96:111], v[204:207], v[172:175], v[96:111]
	ds_read_b128 v[192:195], v210 offset:2048
	ds_read_b128 v[160:163], v208 offset:2048
	v_mfma_f32_32x32x16_bf16 v[80:95], v[200:203], v[176:179], v[80:95]
	ds_read_b128 v[164:167], v208 offset:4096
	ds_read_b128 v[168:171], v208 offset:6144
	v_mfma_f32_32x32x16_bf16 v[64:79], v[204:207], v[176:179], v[64:79]
	s_add_u32 m0, s32, 0x8000
	s_nop 0
	global_load_lds_dwordx4 v[216:217], off
	v_lshl_add_u64 v[216:217], v[216:217], 0, s[10:11]
	v_mfma_f32_32x32x16_bf16 v[48:63], v[200:203], v[180:183], v[48:63]
	v_mfma_f32_32x32x16_bf16 v[32:47], v[204:207], v[180:183], v[32:47]
	v_mfma_f32_32x32x16_bf16 v[16:31], v[200:203], v[184:187], v[16:31]
	v_mfma_f32_32x32x16_bf16 v[0:15], v[204:207], v[184:187], v[0:15]
	s_add_u32 m0, s32, 0xc000
	s_nop 0
	global_load_lds_dwordx4 v[220:221], off
	v_lshl_add_u64 v[220:221], v[220:221], 0, s[10:11]
	s_waitcnt lgkmcnt(0)
	v_mfma_f32_32x32x16_bf16 v[112:127], v[188:191], v[156:159], v[112:127]
	ds_read_b128 v[200:203], v211
	ds_read_b128 v[172:175], v209
	v_mfma_f32_32x32x16_bf16 v[96:111], v[192:195], v[156:159], v[96:111]
	ds_read_b128 v[204:207], v211 offset:2048
	ds_read_b128 v[176:179], v209 offset:2048
	v_mfma_f32_32x32x16_bf16 v[80:95], v[188:191], v[160:163], v[80:95]
	ds_read_b128 v[180:183], v209 offset:4096
	ds_read_b128 v[184:187], v209 offset:6144
	v_mfma_f32_32x32x16_bf16 v[64:79], v[192:195], v[160:163], v[64:79]
	s_add_u32 m0, s32, 0xa000
	s_nop 0
	global_load_lds_dwordx4 v[218:219], off
	v_lshl_add_u64 v[218:219], v[218:219], 0, s[10:11]
	v_mfma_f32_32x32x16_bf16 v[48:63], v[188:191], v[164:167], v[48:63]
	v_mfma_f32_32x32x16_bf16 v[32:47], v[192:195], v[164:167], v[32:47]
	v_mfma_f32_32x32x16_bf16 v[16:31], v[188:191], v[168:171], v[16:31]
	v_mfma_f32_32x32x16_bf16 v[0:15], v[192:195], v[168:171], v[0:15]
	s_add_u32 m0, s32, 0xe000
	s_nop 0
	global_load_lds_dwordx4 v[222:223], off
	v_lshl_add_u64 v[222:223], v[222:223], 0, s[10:11]
	s_waitcnt lgkmcnt(0)
	s_waitcnt vmcnt(12)
	s_barrier
; #define G_LOADA(kt_) { _Pragma("unroll") for (int i = 0; i < 4; ++i) ra[i] = al(lrow + 64 * i, (kt_) * 64 + lck * 8); }
; #define G_LOADB(kt_) { _Pragma("unroll") for (int i = 0; i < 4; ++i) rb[i] = bl(lrow + 64 * i, (kt_) * 64 + lck * 8); }
; #define G_STOREA(buf_) { bf16_t* nA = sA + (buf_) * 256 * GLD; _Pragma("unroll") for (int i = 0; i < 4; ++i) *(u32x4*)(nA + (lrow + 64 * i) * GLD + lck * 8) = ra[i]; }
; #define G_STOREB(buf_) { bf16_t* nB = sB + (buf_) * 256 * GLD; _Pragma("unroll") for (int i = 0; i < 4; ++i) *(u32x4*)(nB + (lrow + 64 * i) * GLD + lck * 8) = rb[i]; }
; template <class AL, class BL, class EP>
; DI void gemm_tile256(AL al, BL bl, EP ep, int K, char* smem) {
;     ...
;   G_LOADA(0); G_LOADB(0);
;   __syncthreads();
;   G_STOREA(0); G_STOREB(0);
;   if (KT > 1) G_LOADB(1);
;   __syncthreads();
;   for (int kt = 0; kt < KT; kt += 2) {
;     G_STEP(0, kt);
;     if (kt + 1 >= KT) break;
;     G_STEP(1, kt + 1);
;   }
	s_waitcnt lgkmcnt(0)
	v_mfma_f32_32x32x16_bf16 v[112:127], v[200:203], v[172:175], v[112:127]
	ds_read_b128 v[188:191], v210 offset:32768
	ds_read_b128 v[156:159], v208 offset:32768
	v_mfma_f32_32x32x16_bf16 v[96:111], v[204:207], v[172:175], v[96:111]
	ds_read_b128 v[192:195], v210 offset:34816
	ds_read_b128 v[160:163], v208 offset:34816
	v_mfma_f32_32x32x16_bf16 v[80:95], v[200:203], v[176:179], v[80:95]
	ds_read_b128 v[164:167], v208 offset:36864
	ds_read_b128 v[168:171], v208 offset:38912
	v_mfma_f32_32x32x16_bf16 v[64:79], v[204:207], v[176:179], v[64:79]
	v_mfma_f32_32x32x16_bf16 v[48:63], v[200:203], v[180:183], v[48:63]
	v_mfma_f32_32x32x16_bf16 v[32:47], v[204:207], v[180:183], v[32:47]
	v_mfma_f32_32x32x16_bf16 v[16:31], v[200:203], v[184:187], v[16:31]
	v_mfma_f32_32x32x16_bf16 v[0:15], v[204:207], v[184:187], v[0:15]
	s_waitcnt lgkmcnt(0)
	v_mfma_f32_32x32x16_bf16 v[112:127], v[188:191], v[156:159], v[112:127]
	ds_read_b128 v[200:203], v211 offset:32768
	ds_read_b128 v[172:175], v209 offset:32768
	v_mfma_f32_32x32x16_bf16 v[96:111], v[192:195], v[156:159], v[96:111]
	ds_read_b128 v[204:207], v211 offset:34816
	ds_read_b128 v[176:179], v209 offset:34816
	v_mfma_f32_32x32x16_bf16 v[80:95], v[188:191], v[160:163], v[80:95]
	ds_read_b128 v[180:183], v209 offset:36864
	ds_read_b128 v[184:187], v209 offset:38912
	v_mfma_f32_32x32x16_bf16 v[64:79], v[192:195], v[160:163], v[64:79]
	v_mfma_f32_32x32x16_bf16 v[48:63], v[188:191], v[164:167], v[48:63]
	v_mfma_f32_32x32x16_bf16 v[32:47], v[192:195], v[164:167], v[32:47]
	v_mfma_f32_32x32x16_bf16 v[16:31], v[188:191], v[168:171], v[16:31]
	v_mfma_f32_32x32x16_bf16 v[0:15], v[192:195], v[168:171], v[0:15]
	s_waitcnt lgkmcnt(0)
	s_waitcnt vmcnt(8)
	s_barrier
	s_waitcnt lgkmcnt(0)
	v_mfma_f32_32x32x16_bf16 v[112:127], v[200:203], v[172:175], v[112:127]
	ds_read_b128 v[188:191], v214
	ds_read_b128 v[156:159], v212
	v_mfma_f32_32x32x16_bf16 v[96:111], v[204:207], v[172:175], v[96:111]
	ds_read_b128 v[192:195], v214 offset:2048
	ds_read_b128 v[160:163], v212 offset:2048
	v_mfma_f32_32x32x16_bf16 v[80:95], v[200:203], v[176:179], v[80:95]
	ds_read_b128 v[164:167], v212 offset:4096
	ds_read_b128 v[168:171], v212 offset:6144
	v_mfma_f32_32x32x16_bf16 v[64:79], v[204:207], v[176:179], v[64:79]
	v_mfma_f32_32x32x16_bf16 v[48:63], v[200:203], v[180:183], v[48:63]
	v_mfma_f32_32x32x16_bf16 v[32:47], v[204:207], v[180:183], v[32:47]
	v_mfma_f32_32x32x16_bf16 v[16:31], v[200:203], v[184:187], v[16:31]
	v_mfma_f32_32x32x16_bf16 v[0:15], v[204:207], v[184:187], v[0:15]
	s_waitcnt lgkmcnt(0)
	v_mfma_f32_32x32x16_bf16 v[112:127], v[188:191], v[156:159], v[112:127]
	ds_read_b128 v[200:203], v215
	ds_read_b128 v[172:175], v213
	v_mfma_f32_32x32x16_bf16 v[96:111], v[192:195], v[156:159], v[96:111]
	ds_read_b128 v[204:207], v215 offset:2048
	ds_read_b128 v[176:179], v213 offset:2048
	v_mfma_f32_32x32x16_bf16 v[80:95], v[188:191], v[160:163], v[80:95]
	ds_read_b128 v[180:183], v213 offset:4096
	ds_read_b128 v[184:187], v213 offset:6144
	v_mfma_f32_32x32x16_bf16 v[64:79], v[192:195], v[160:163], v[64:79]
	v_mfma_f32_32x32x16_bf16 v[48:63], v[188:191], v[164:167], v[48:63]
	v_mfma_f32_32x32x16_bf16 v[32:47], v[192:195], v[164:167], v[32:47]
	v_mfma_f32_32x32x16_bf16 v[16:31], v[188:191], v[168:171], v[16:31]
	v_mfma_f32_32x32x16_bf16 v[0:15], v[192:195], v[168:171], v[0:15]
	s_waitcnt lgkmcnt(0)
	s_waitcnt vmcnt(4)
	s_barrier
	s_waitcnt lgkmcnt(0)
	v_mfma_f32_32x32x16_bf16 v[112:127], v[200:203], v[172:175], v[112:127]
	ds_read_b128 v[188:191], v198
	ds_read_b128 v[156:159], v134
	v_mfma_f32_32x32x16_bf16 v[96:111], v[204:207], v[172:175], v[96:111]
	ds_read_b128 v[192:195], v198 offset:2048
	ds_read_b128 v[160:163], v134 offset:2048
	v_mfma_f32_32x32x16_bf16 v[80:95], v[200:203], v[176:179], v[80:95]
	ds_read_b128 v[164:167], v134 offset:4096
	ds_read_b128 v[168:171], v134 offset:6144
	v_mfma_f32_32x32x16_bf16 v[64:79], v[204:207], v[176:179], v[64:79]
	v_mfma_f32_32x32x16_bf16 v[48:63], v[200:203], v[180:183], v[48:63]
	v_mfma_f32_32x32x16_bf16 v[32:47], v[204:207], v[180:183], v[32:47]
	v_mfma_f32_32x32x16_bf16 v[16:31], v[200:203], v[184:187], v[16:31]
	v_mfma_f32_32x32x16_bf16 v[0:15], v[204:207], v[184:187], v[0:15]
	s_waitcnt lgkmcnt(0)
	v_mfma_f32_32x32x16_bf16 v[112:127], v[188:191], v[156:159], v[112:127]
	ds_read_b128 v[200:203], v199
	ds_read_b128 v[172:175], v155
	v_mfma_f32_32x32x16_bf16 v[96:111], v[192:195], v[156:159], v[96:111]
	ds_read_b128 v[204:207], v199 offset:2048
	ds_read_b128 v[176:179], v155 offset:2048
	v_mfma_f32_32x32x16_bf16 v[80:95], v[188:191], v[160:163], v[80:95]
	ds_read_b128 v[180:183], v155 offset:4096
	ds_read_b128 v[184:187], v155 offset:6144
	v_mfma_f32_32x32x16_bf16 v[64:79], v[192:195], v[160:163], v[64:79]
	v_mfma_f32_32x32x16_bf16 v[48:63], v[188:191], v[164:167], v[48:63]
	v_mfma_f32_32x32x16_bf16 v[32:47], v[192:195], v[164:167], v[32:47]
	v_mfma_f32_32x32x16_bf16 v[16:31], v[188:191], v[168:171], v[16:31]
	v_mfma_f32_32x32x16_bf16 v[0:15], v[192:195], v[168:171], v[0:15]
	s_waitcnt lgkmcnt(0)
	s_waitcnt vmcnt(0)
	s_barrier
; DI unsigned pack2(float a, float b) { f2_t f = {a, b}; bf2_t r = __builtin_convertvector(f, bf2_t); return __builtin_bit_cast(unsigned, r); }
; template <class AL, class BL, class EP>
; DI void gemm_tile256(AL al, BL bl, EP ep, int K, char* smem) {
;     ...
;     for (int i = 0; i < 4; ++i)
; #pragma unroll
;       for (int j = 0; j < 2; ++j)
; #pragma unroll
;         for (int g = 0; g < 4; ++g) {
;           u32x2 v = {pack2(acc[i][j][4 * g], acc[i][j][4 * g + 1]), pack2(acc[i][j][4 * g + 2], acc[i][j][4 * g + 3])};
;           *(u32x2*)(sCb + (128 * wm + 32 * i + r) * BLD + 64 * wn + 32 * j + 8 * g + 4 * h) = v;
	s_waitcnt lgkmcnt(0)
	v_mfma_f32_32x32x16_bf16 v[112:127], v[200:203], v[172:175], v[112:127]
	ds_read_b128 v[188:191], v198 offset:32768
	ds_read_b128 v[156:159], v134 offset:32768
	v_mfma_f32_32x32x16_bf16 v[96:111], v[204:207], v[172:175], v[96:111]
	ds_read_b128 v[192:195], v198 offset:34816
	ds_read_b128 v[160:163], v134 offset:34816
	v_mfma_f32_32x32x16_bf16 v[80:95], v[200:203], v[176:179], v[80:95]
	ds_read_b128 v[164:167], v134 offset:36864
	ds_read_b128 v[168:171], v134 offset:38912
	v_mfma_f32_32x32x16_bf16 v[64:79], v[204:207], v[176:179], v[64:79]
	v_mfma_f32_32x32x16_bf16 v[48:63], v[200:203], v[180:183], v[48:63]
	v_mfma_f32_32x32x16_bf16 v[32:47], v[204:207], v[180:183], v[32:47]
	v_mfma_f32_32x32x16_bf16 v[16:31], v[200:203], v[184:187], v[16:31]
	v_mfma_f32_32x32x16_bf16 v[0:15], v[204:207], v[184:187], v[0:15]
	s_waitcnt lgkmcnt(0)
	v_mfma_f32_32x32x16_bf16 v[112:127], v[188:191], v[156:159], v[112:127]
	ds_read_b128 v[200:203], v199 offset:32768
	ds_read_b128 v[172:175], v155 offset:32768
	v_mfma_f32_32x32x16_bf16 v[96:111], v[192:195], v[156:159], v[96:111]
	ds_read_b128 v[204:207], v199 offset:34816
	ds_read_b128 v[176:179], v155 offset:34816
	v_mfma_f32_32x32x16_bf16 v[80:95], v[188:191], v[160:163], v[80:95]
	ds_read_b128 v[180:183], v155 offset:36864
	ds_read_b128 v[184:187], v155 offset:38912
	v_mfma_f32_32x32x16_bf16 v[64:79], v[192:195], v[160:163], v[64:79]
	v_mfma_f32_32x32x16_bf16 v[48:63], v[188:191], v[164:167], v[48:63]
	v_mfma_f32_32x32x16_bf16 v[32:47], v[192:195], v[164:167], v[32:47]
	v_mfma_f32_32x32x16_bf16 v[16:31], v[188:191], v[168:171], v[16:31]
	v_mfma_f32_32x32x16_bf16 v[0:15], v[192:195], v[168:171], v[0:15]
	s_waitcnt lgkmcnt(0)
	s_waitcnt lgkmcnt(0)
	v_mfma_f32_32x32x16_bf16 v[112:127], v[200:203], v[172:175], v[112:127]
	v_mfma_f32_32x32x16_bf16 v[96:111], v[204:207], v[172:175], v[96:111]
	v_mfma_f32_32x32x16_bf16 v[80:95], v[200:203], v[176:179], v[80:95]
	v_mfma_f32_32x32x16_bf16 v[64:79], v[204:207], v[176:179], v[64:79]
	v_mfma_f32_32x32x16_bf16 v[48:63], v[200:203], v[180:183], v[48:63]
	v_mfma_f32_32x32x16_bf16 v[32:47], v[204:207], v[180:183], v[32:47]
	v_mfma_f32_32x32x16_bf16 v[16:31], v[200:203], v[184:187], v[16:31]
	v_mfma_f32_32x32x16_bf16 v[0:15], v[204:207], v[184:187], v[0:15]
	s_nop 15
	s_nop 3
	s_waitcnt lgkmcnt(4)
	v_lshl_or_b32 v128, v135, 7, v154
	v_mad_u64_u32 v[132:133], s[0:1], v153, s25, v[128:129]
	s_waitcnt lgkmcnt(0)
	s_barrier
; DI unsigned pack2(float a, float b) { f2_t f = {a, b}; bf2_t r = __builtin_convertvector(f, bf2_t); return __builtin_bit_cast(unsigned, r); }
; DI int tid512() { int t = threadIdx_x_raw(); asm volatile("" : "+v"(t)); return t; }
; template <class AL, class BL, class EP>
; DI void gemm_tile256(AL al, BL bl, EP ep, int K, char* smem) {
;     ...
;     for (int i = 0; i < 4; ++i)
; #pragma unroll
;       for (int j = 0; j < 2; ++j)
; #pragma unroll
;         for (int g = 0; g < 4; ++g) {
;           u32x2 v = {pack2(acc[i][j][4 * g], acc[i][j][4 * g + 1]), pack2(acc[i][j][4 * g + 2], acc[i][j][4 * g + 3])};
;           *(u32x2*)(sCb + (128 * wm + 32 * i + r) * BLD + 64 * wn + 32 * j + 8 * g + 4 * h) = v;
;         }
;     __syncthreads();
;   DI void operator()(const bf16_t* sCb) const {
;     const int t = tid512(), hf = (t >> 3) & 1, c8 = (t & 7) * 8;
;     const int cb = c0 + 64 * hf;
;     const bf16_t* base = sCb + 128 * hf;
;     float w0[8], w1[8], w2[8];
;     ld8f(conv + cb + c8, w0); ld8f(conv + DFF + cb + c8, w1); ld8f(conv + 2 * DFF + cb + c8, w2);
;     for (int rr = t >> 4; rr < 254; rr += 32) {
	v_lshlrev_b32_e32 v131, 7, v131
	v_bfe_u32 v200, v196, 3, 1
	v_lshlrev_b32_e32 v200, 6, v200
	v_or_b32_e32 v200, v200, v131
	v_ashrrev_i32_e32 v201, 31, v200
	v_lshlrev_b64 v[200:201], 2, v[200:201]
	v_lshlrev_b32_e32 v202, 3, v196
	v_and_b32_e32 v202, 56, v202
	v_lshlrev_b32_e32 v202, 2, v202
	v_mov_b32_e32 v203, 0
	v_lshl_add_u64 v[204:205], s[14:15], 0, v[200:201]
	v_lshl_add_u64 v[204:205], v[204:205], 0, v[202:203]
	v_lshl_add_u64 v[206:207], s[6:7], 0, v[200:201]
	v_lshl_add_u64 v[206:207], v[206:207], 0, v[202:203]
	v_lshl_add_u64 v[240:241], s[4:5], 0, v[200:201]
	v_lshl_add_u64 v[240:241], v[240:241], 0, v[202:203]
	global_load_dwordx4 v[208:211], v[204:205], off
	global_load_dwordx4 v[212:215], v[204:205], off offset:16
	global_load_dwordx4 v[216:219], v[206:207], off
	global_load_dwordx4 v[220:223], v[206:207], off offset:16
	global_load_dwordx4 v[224:227], v[240:241], off
	global_load_dwordx4 v[228:231], v[240:241], off offset:16
	s_nop 5
	v_cvt_pk_bf16_f32 v112, v112, v113
	v_cvt_pk_bf16_f32 v113, v114, v115
	v_cvt_pk_bf16_f32 v114, v116, v117
	v_cvt_pk_bf16_f32 v115, v118, v119
	ds_write2_b64 v132, v[112:113], v[114:115] offset1:2
	v_cvt_pk_bf16_f32 v112, v120, v121
	v_cvt_pk_bf16_f32 v113, v122, v123
	v_cvt_pk_bf16_f32 v96, v96, v97
	v_cvt_pk_bf16_f32 v97, v98, v99
	v_cvt_pk_bf16_f32 v98, v100, v101
	v_cvt_pk_bf16_f32 v99, v102, v103
	v_cvt_pk_bf16_f32 v114, v124, v125
	v_cvt_pk_bf16_f32 v115, v126, v127
	ds_write2_b64 v132, v[96:97], v[98:99] offset0:8 offset1:10
	s_nop 3
	v_cvt_pk_bf16_f32 v80, v80, v81
	v_cvt_pk_bf16_f32 v81, v82, v83
	v_cvt_pk_bf16_f32 v82, v84, v85
	v_cvt_pk_bf16_f32 v83, v86, v87
	v_add_u32_e32 v84, 0x4000, v132
	v_cvt_pk_bf16_f32 v96, v104, v105
	v_cvt_pk_bf16_f32 v97, v106, v107
	v_cvt_pk_bf16_f32 v64, v64, v65
	v_cvt_pk_bf16_f32 v65, v66, v67
	v_cvt_pk_bf16_f32 v66, v68, v69
	v_cvt_pk_bf16_f32 v67, v70, v71
	v_cvt_pk_bf16_f32 v98, v108, v109
	v_cvt_pk_bf16_f32 v99, v110, v111
	ds_write2_b64 v84, v[80:81], v[82:83] offset0:64 offset1:66
	s_nop 3
	v_cvt_pk_bf16_f32 v48, v48, v49
	v_cvt_pk_bf16_f32 v49, v50, v51
	v_cvt_pk_bf16_f32 v50, v52, v53
	v_cvt_pk_bf16_f32 v51, v54, v55
	v_add_u32_e32 v52, 0x8000, v132
	v_cvt_pk_bf16_f32 v80, v88, v89
	v_cvt_pk_bf16_f32 v81, v90, v91
	v_cvt_pk_bf16_f32 v32, v32, v33
	v_cvt_pk_bf16_f32 v33, v34, v35
	v_cvt_pk_bf16_f32 v34, v36, v37
	v_cvt_pk_bf16_f32 v35, v38, v39
	v_cvt_pk_bf16_f32 v82, v92, v93
	v_cvt_pk_bf16_f32 v83, v94, v95
	ds_write2_b64 v84, v[64:65], v[66:67] offset0:72 offset1:74
	s_nop 3
	v_cvt_pk_bf16_f32 v16, v16, v17
	v_cvt_pk_bf16_f32 v17, v18, v19
	v_cvt_pk_bf16_f32 v18, v20, v21
	v_cvt_pk_bf16_f32 v19, v22, v23
	v_add_u32_e32 v20, 0xc000, v132
	v_cvt_pk_bf16_f32 v64, v72, v73
	v_cvt_pk_bf16_f32 v65, v74, v75
	s_nop 0
	v_cvt_pk_bf16_f32 v0, v0, v1
	v_cvt_pk_bf16_f32 v1, v2, v3
	v_cvt_pk_bf16_f32 v2, v4, v5
	v_cvt_pk_bf16_f32 v3, v6, v7
	v_cvt_pk_bf16_f32 v66, v76, v77
	v_cvt_pk_bf16_f32 v67, v78, v79
	ds_write2_b64 v52, v[48:49], v[50:51] offset0:128 offset1:130
	v_cvt_pk_bf16_f32 v48, v56, v57
	v_cvt_pk_bf16_f32 v49, v58, v59
	v_cvt_pk_bf16_f32 v50, v60, v61
	v_cvt_pk_bf16_f32 v51, v62, v63
	ds_write2_b64 v52, v[32:33], v[34:35] offset0:136 offset1:138
	v_cvt_pk_bf16_f32 v32, v40, v41
	v_cvt_pk_bf16_f32 v33, v42, v43
	v_cvt_pk_bf16_f32 v34, v44, v45
	v_cvt_pk_bf16_f32 v35, v46, v47
	ds_write2_b64 v20, v[16:17], v[18:19] offset0:192 offset1:194
	v_cvt_pk_bf16_f32 v16, v24, v25
	v_cvt_pk_bf16_f32 v17, v26, v27
	v_cvt_pk_bf16_f32 v18, v28, v29
	v_cvt_pk_bf16_f32 v19, v30, v31
	ds_write2_b64 v20, v[0:1], v[2:3] offset0:200 offset1:202
	v_cvt_pk_bf16_f32 v0, v8, v9
	v_cvt_pk_bf16_f32 v1, v10, v11
	v_cvt_pk_bf16_f32 v2, v12, v13
	v_cvt_pk_bf16_f32 v3, v14, v15
	v_mov_b32_e32 v29, v196
	ds_write2_b64 v132, v[112:113], v[114:115] offset0:4 offset1:6
	ds_write2_b64 v132, v[96:97], v[98:99] offset0:12 offset1:14
	ds_write2_b64 v84, v[80:81], v[82:83] offset0:68 offset1:70
	ds_write2_b64 v84, v[64:65], v[66:67] offset0:76 offset1:78
	ds_write2_b64 v52, v[48:49], v[50:51] offset0:132 offset1:134
	ds_write2_b64 v52, v[32:33], v[34:35] offset0:140 offset1:142
	ds_write2_b64 v20, v[16:17], v[18:19] offset0:196 offset1:198
	ds_write2_b64 v20, v[0:1], v[2:3] offset0:204 offset1:206
	s_waitcnt lgkmcnt(0)
	s_barrier
	s_nop 0
	v_bfe_u32 v0, v29, 3, 1
	v_lshlrev_b32_e32 v30, 6, v0
	v_lshlrev_b32_e32 v1, 3, v29
	v_or_b32_e32 v24, v30, v131
	v_ashrrev_i32_e32 v26, 4, v29
	v_and_b32_e32 v27, 56, v1
	v_lshlrev_b32_e32 v28, 8, v0
	v_ashrrev_i32_e32 v25, 31, v24
	v_cmp_gt_i32_e32 vcc, s26, v26
	s_and_saveexec_b64 s[0:1], vcc
	s_cbranch_execz .LBB0_1147
	v_lshlrev_b64 v[16:17], 2, v[24:25]
	v_lshl_add_u64 v[0:1], s[14:15], 0, v[16:17]
	v_lshlrev_b32_e32 v128, 2, v27
	v_lshl_add_u64 v[8:9], s[6:7], 0, v[16:17]
	v_lshl_add_u64 v[16:17], s[4:5], 0, v[16:17]
	v_lshl_add_u64 v[4:5], v[0:1], 0, v[128:129]
	v_lshl_add_u64 v[12:13], v[8:9], 0, v[128:129]
	v_lshl_add_u64 v[20:21], v[16:17], 0, v[128:129]
	s_waitcnt vmcnt(0)
	v_mov_b32_e32 v0, v208
	v_mov_b32_e32 v1, v209
	v_mov_b32_e32 v2, v210
	v_mov_b32_e32 v3, v211
	v_mov_b32_e32 v4, v212
	v_mov_b32_e32 v5, v213
	v_mov_b32_e32 v6, v214
	v_mov_b32_e32 v7, v215
	v_mov_b32_e32 v8, v216
	v_mov_b32_e32 v9, v217
	v_mov_b32_e32 v10, v218
	v_mov_b32_e32 v11, v219
	v_mov_b32_e32 v12, v220
	v_mov_b32_e32 v13, v221
	v_mov_b32_e32 v14, v222
	v_mov_b32_e32 v15, v223
	v_mov_b32_e32 v16, v224
	v_mov_b32_e32 v17, v225
	v_mov_b32_e32 v18, v226
	v_mov_b32_e32 v19, v227
	v_mov_b32_e32 v20, v228
	v_mov_b32_e32 v21, v229
	v_mov_b32_e32 v22, v230
	v_mov_b32_e32 v23, v231
	v_lshlrev_b32_e32 v33, 4, v29
	v_mad_i64_i32 v[34:35], s[18:19], v26, s27, 0
	v_mul_lo_u32 v31, v26, s25
	v_and_b32_e32 v36, 0x70, v33
	v_mad_i64_i32 v[34:35], s[18:19], v130, s28, v[34:35]
	v_add_u32_e32 v30, v131, v30
	v_add3_u32 v33, v31, v28, v36
	v_or_b32_e32 v34, v34, v36
	v_ashrrev_i32_e32 v31, 31, v30
	v_readlane_b32 s10, v246, 51
	v_lshl_add_u64 v[30:31], v[30:31], 1, v[34:35]
	v_readlane_b32 s11, v246, 52
	v_subrev_u32_e32 v32, 32, v26
	s_mov_b64 s[18:19], 0
	v_lshl_add_u64 v[30:31], s[10:11], 0, v[30:31]
	s_waitcnt vmcnt(0)
